# GEMM tiles: accumulators start from SrcC=0 in a peeled first iteration (no per-tile re-zeroing), on top of combined v25
# speedup vs baseline: 1.0101x; 1.0046x over previous
.LBB0_187:
	s_ashr_i32 s15, s14, 31
	s_lshl_b64 s[16:17], s[14:15], 19
	s_add_u32 s16, s30, s16
	s_addc_u32 s17, s31, s17
	s_and_b64 s[18:19], s[0:1], exec
	s_cselect_b32 s3, s17, s25
	s_cselect_b32 s15, s16, s24
	s_ashr_i32 s13, s12, 31
	s_lshl_b64 s[18:19], s[12:13], 19
	s_add_u32 s18, s34, s18
	s_addc_u32 s19, s35, s19
	s_and_b64 s[26:27], s[0:1], exec
	s_cselect_b32 s13, s19, s23
	s_cselect_b32 s21, s18, s22
	s_add_u32 s48, s22, 0x100
	s_addc_u32 s49, s23, 0
	s_add_u32 s22, s24, 0x40080
	s_addc_u32 s23, s25, 0
	s_mov_b32 s50, -2
	s_waitcnt vmcnt(0)
	s_add_u32 s24, s22, 0xfffc0080
	s_addc_u32 s25, s23, -1
	s_add_i32 s51, 0, 0x10000
	s_cmp_eq_u32 s50, 12
	s_cselect_b32 s27, s3, s25
	s_cselect_b32 s26, s15, s24
	v_add_u32_e32 v142, s51, v144
	s_cselect_b32 s25, s13, s49
	s_cselect_b32 s24, s21, s48
	s_add_i32 s54, 0, 0x14000
	ds_read_b128 v[138:141], v142
	ds_read_b128 v[146:149], v142 offset:1024
	ds_read_b128 v[150:153], v142 offset:2048
	ds_read_b128 v[154:157], v142 offset:3072
	v_add_u32_e32 v142, s54, v144
	ds_read_b128 v[158:161], v142
	ds_read_b128 v[162:165], v142 offset:1024
	ds_read_b128 v[166:169], v142 offset:2048
	ds_read_b128 v[170:173], v142 offset:3072
	v_lshl_add_u64 v[142:143], s[22:23], 0, v[136:137]
	s_add_i32 m0, s37, 0xc000
	ds_read_b128 v[174:177], v145
	ds_read_b128 v[178:181], v145 offset:1024
	ds_read_b128 v[182:185], v145 offset:2048
	ds_read_b128 v[186:189], v145 offset:3072
	ds_read_b128 v[190:193], v145 offset:4096
	ds_read_b128 v[194:197], v145 offset:5120
	ds_read_b128 v[198:201], v145 offset:6144
	ds_read_b128 v[202:205], v145 offset:7168
	global_load_lds_dwordx4 v[142:143], off
	v_lshl_add_u64 v[142:143], s[22:23], 0, v[134:135]
	s_add_i32 m0, s37, 0xe000
	s_nop 0
	global_load_lds_dwordx4 v[142:143], off
	s_waitcnt vmcnt(8)
	s_waitcnt lgkmcnt(0)
	s_barrier
	s_setprio 1
	s_waitcnt lgkmcnt(0)
	v_mfma_f32_16x16x32_bf16 v[124:127], v[138:141], v[174:177], 0
	v_mfma_f32_16x16x32_bf16 v[120:123], v[150:153], v[174:177], 0
	v_mfma_f32_16x16x32_bf16 v[112:115], v[138:141], v[182:185], 0
	v_mfma_f32_16x16x32_bf16 v[104:107], v[150:153], v[182:185], 0
	v_mfma_f32_16x16x32_bf16 v[96:99], v[138:141], v[190:193], 0
	v_mfma_f32_16x16x32_bf16 v[88:91], v[150:153], v[190:193], 0
	v_mfma_f32_16x16x32_bf16 v[80:83], v[138:141], v[198:201], 0
	v_mfma_f32_16x16x32_bf16 v[72:75], v[150:153], v[198:201], 0
	v_mfma_f32_16x16x32_bf16 v[124:127], v[146:149], v[178:181], v[124:127]
	v_mfma_f32_16x16x32_bf16 v[120:123], v[154:157], v[178:181], v[120:123]
	v_mfma_f32_16x16x32_bf16 v[112:115], v[146:149], v[186:189], v[112:115]
	v_mfma_f32_16x16x32_bf16 v[104:107], v[154:157], v[186:189], v[104:107]
	v_mfma_f32_16x16x32_bf16 v[96:99], v[146:149], v[194:197], v[96:99]
	v_mfma_f32_16x16x32_bf16 v[88:91], v[154:157], v[194:197], v[88:91]
	v_mfma_f32_16x16x32_bf16 v[80:83], v[146:149], v[202:205], v[80:83]
	v_mfma_f32_16x16x32_bf16 v[72:75], v[154:157], v[202:205], v[72:75]
	s_setprio 0
	s_setprio 1
	v_mfma_f32_16x16x32_bf16 v[116:119], v[158:161], v[174:177], 0
	v_mfma_f32_16x16x32_bf16 v[108:111], v[166:169], v[174:177], 0
	v_mfma_f32_16x16x32_bf16 v[100:103], v[158:161], v[182:185], 0
	v_mfma_f32_16x16x32_bf16 v[92:95], v[166:169], v[182:185], 0
	v_mfma_f32_16x16x32_bf16 v[84:87], v[158:161], v[190:193], 0
	v_mfma_f32_16x16x32_bf16 v[76:79], v[166:169], v[190:193], 0
	v_mfma_f32_16x16x32_bf16 v[68:71], v[158:161], v[198:201], 0
	v_mfma_f32_16x16x32_bf16 v[64:67], v[166:169], v[198:201], 0
	v_mfma_f32_16x16x32_bf16 v[116:119], v[162:165], v[178:181], v[116:119]
	v_mfma_f32_16x16x32_bf16 v[108:111], v[170:173], v[178:181], v[108:111]
	v_mfma_f32_16x16x32_bf16 v[100:103], v[162:165], v[186:189], v[100:103]
	v_mfma_f32_16x16x32_bf16 v[92:95], v[170:173], v[186:189], v[92:95]
	v_mfma_f32_16x16x32_bf16 v[84:87], v[162:165], v[194:197], v[84:87]
	v_mfma_f32_16x16x32_bf16 v[76:79], v[170:173], v[194:197], v[76:79]
	v_mfma_f32_16x16x32_bf16 v[68:71], v[162:165], v[202:205], v[68:71]
	v_mfma_f32_16x16x32_bf16 v[64:67], v[170:173], v[202:205], v[64:67]
	s_setprio 0
	s_barrier
	s_add_i32 s51, s51, s36
	v_lshl_add_u64 v[142:143], s[24:25], 0, v[232:233]
	s_mov_b32 m0, s51
	ds_read_b128 v[174:177], v145 offset:16384
	ds_read_b128 v[178:181], v145 offset:17408
	ds_read_b128 v[182:185], v145 offset:18432
	ds_read_b128 v[186:189], v145 offset:19456
	ds_read_b128 v[190:193], v145 offset:20480
	ds_read_b128 v[194:197], v145 offset:21504
	ds_read_b128 v[198:201], v145 offset:22528
	ds_read_b128 v[202:205], v145 offset:23552
	global_load_lds_dwordx4 v[142:143], off
	s_add_i32 m0, s51, 0x2000
	s_add_u32 s52, s24, 0x40000
	v_lshl_add_u64 v[206:207], s[24:25], 0, v[132:133]
	s_addc_u32 s53, s25, 0
	s_add_i32 s51, s54, s36
	global_load_lds_dwordx4 v[206:207], off
	v_lshl_add_u64 v[208:209], s[52:53], 0, v[232:233]
	s_mov_b32 m0, s51
	v_lshl_add_u64 v[210:211], s[26:27], 0, v[130:131]
	global_load_lds_dwordx4 v[208:209], off
	v_lshl_add_u64 v[208:209], s[52:53], 0, v[132:133]
	s_add_i32 m0, s51, 0x2000
	s_nop 0
	global_load_lds_dwordx4 v[208:209], off
	v_lshl_add_u64 v[208:209], s[26:27], 0, v[128:129]
	s_waitcnt vmcnt(6)
	s_waitcnt lgkmcnt(0)
	s_barrier
	s_setprio 1
	s_waitcnt lgkmcnt(0)
	v_mfma_f32_16x16x32_bf16 v[60:63], v[138:141], v[174:177], 0
	v_mfma_f32_16x16x32_bf16 v[56:59], v[150:153], v[174:177], 0
	v_mfma_f32_16x16x32_bf16 v[48:51], v[138:141], v[182:185], 0
	v_mfma_f32_16x16x32_bf16 v[40:43], v[150:153], v[182:185], 0
	v_mfma_f32_16x16x32_bf16 v[32:35], v[138:141], v[190:193], 0
	v_mfma_f32_16x16x32_bf16 v[24:27], v[150:153], v[190:193], 0
	v_mfma_f32_16x16x32_bf16 v[16:19], v[138:141], v[198:201], 0
	v_mfma_f32_16x16x32_bf16 v[8:11], v[150:153], v[198:201], 0
	v_mfma_f32_16x16x32_bf16 v[60:63], v[146:149], v[178:181], v[60:63]
	v_mfma_f32_16x16x32_bf16 v[56:59], v[154:157], v[178:181], v[56:59]
	v_mfma_f32_16x16x32_bf16 v[48:51], v[146:149], v[186:189], v[48:51]
	v_mfma_f32_16x16x32_bf16 v[40:43], v[154:157], v[186:189], v[40:43]
	v_mfma_f32_16x16x32_bf16 v[32:35], v[146:149], v[194:197], v[32:35]
	v_mfma_f32_16x16x32_bf16 v[24:27], v[154:157], v[194:197], v[24:27]
	v_mfma_f32_16x16x32_bf16 v[16:19], v[146:149], v[202:205], v[16:19]
	v_mfma_f32_16x16x32_bf16 v[8:11], v[154:157], v[202:205], v[8:11]
	s_setprio 0
	s_setprio 1
	v_mfma_f32_16x16x32_bf16 v[52:55], v[158:161], v[174:177], 0
	v_mfma_f32_16x16x32_bf16 v[44:47], v[166:169], v[174:177], 0
	v_mfma_f32_16x16x32_bf16 v[36:39], v[158:161], v[182:185], 0
	v_mfma_f32_16x16x32_bf16 v[28:31], v[166:169], v[182:185], 0
	v_mfma_f32_16x16x32_bf16 v[20:23], v[158:161], v[190:193], 0
	v_mfma_f32_16x16x32_bf16 v[12:15], v[166:169], v[190:193], 0
	v_mfma_f32_16x16x32_bf16 v[4:7], v[158:161], v[198:201], 0
	v_mfma_f32_16x16x32_bf16 v[0:3], v[166:169], v[198:201], 0
	v_mfma_f32_16x16x32_bf16 v[52:55], v[162:165], v[178:181], v[52:55]
	v_mfma_f32_16x16x32_bf16 v[44:47], v[170:173], v[178:181], v[44:47]
	v_mfma_f32_16x16x32_bf16 v[36:39], v[162:165], v[186:189], v[36:39]
	v_mfma_f32_16x16x32_bf16 v[28:31], v[170:173], v[186:189], v[28:31]
	v_mfma_f32_16x16x32_bf16 v[20:23], v[162:165], v[194:197], v[20:23]
	v_mfma_f32_16x16x32_bf16 v[12:15], v[170:173], v[194:197], v[12:15]
	v_mfma_f32_16x16x32_bf16 v[4:7], v[162:165], v[202:205], v[4:7]
	v_mfma_f32_16x16x32_bf16 v[0:3], v[170:173], v[202:205], v[0:3]
	s_setprio 0
	s_barrier
	s_branch .Lzmid_1

.Lzmid_1:
	s_add_i32 s51, 0, 0x18000
	s_add_i32 s52, 0, 0x1c000
	v_add_u32_e32 v154, s51, v144
	v_add_u32_e32 v170, s52, v144
	ds_read_b128 v[138:141], v154
	ds_read_b128 v[146:149], v154 offset:1024
	ds_read_b128 v[150:153], v154 offset:2048
	ds_read_b128 v[154:157], v154 offset:3072
	ds_read_b128 v[158:161], v170
	ds_read_b128 v[162:165], v170 offset:1024
	ds_read_b128 v[166:169], v170 offset:2048
	ds_read_b128 v[170:173], v170 offset:3072
	s_add_u32 s26, s26, 0x40000
	s_addc_u32 s27, s27, 0
	s_mov_b32 m0, s37
	s_nop 0
	global_load_lds_dwordx4 v[208:209], off
	s_mov_b32 m0, s38
	s_nop 0
	global_load_lds_dwordx4 v[210:211], off
	s_mov_b32 m0, s39
	v_lshl_add_u64 v[212:213], s[26:27], 0, v[128:129]
	ds_read_b128 v[174:177], v145 offset:32768
	ds_read_b128 v[178:181], v145 offset:33792
	ds_read_b128 v[182:185], v145 offset:34816
	ds_read_b128 v[186:189], v145 offset:35840
	ds_read_b128 v[190:193], v145 offset:36864
	ds_read_b128 v[194:197], v145 offset:37888
	ds_read_b128 v[198:201], v145 offset:38912
	ds_read_b128 v[202:205], v145 offset:39936
	global_load_lds_dwordx4 v[212:213], off
	v_lshl_add_u64 v[212:213], s[26:27], 0, v[130:131]
	s_mov_b32 m0, s40
	s_nop 0
	global_load_lds_dwordx4 v[212:213], off
	s_waitcnt vmcnt(8)
	s_waitcnt lgkmcnt(0)
	s_barrier
	s_setprio 1
	s_waitcnt lgkmcnt(0)
	v_mfma_f32_16x16x32_bf16 v[124:127], v[138:141], v[174:177], v[124:127]
	v_mfma_f32_16x16x32_bf16 v[120:123], v[150:153], v[174:177], v[120:123]
	v_mfma_f32_16x16x32_bf16 v[112:115], v[138:141], v[182:185], v[112:115]
	v_mfma_f32_16x16x32_bf16 v[104:107], v[150:153], v[182:185], v[104:107]
	v_mfma_f32_16x16x32_bf16 v[96:99], v[138:141], v[190:193], v[96:99]
	v_mfma_f32_16x16x32_bf16 v[88:91], v[150:153], v[190:193], v[88:91]
	v_mfma_f32_16x16x32_bf16 v[80:83], v[138:141], v[198:201], v[80:83]
	v_mfma_f32_16x16x32_bf16 v[72:75], v[150:153], v[198:201], v[72:75]
	v_mfma_f32_16x16x32_bf16 v[124:127], v[146:149], v[178:181], v[124:127]
	v_mfma_f32_16x16x32_bf16 v[120:123], v[154:157], v[178:181], v[120:123]
	v_mfma_f32_16x16x32_bf16 v[112:115], v[146:149], v[186:189], v[112:115]
	v_mfma_f32_16x16x32_bf16 v[104:107], v[154:157], v[186:189], v[104:107]
	v_mfma_f32_16x16x32_bf16 v[96:99], v[146:149], v[194:197], v[96:99]
	v_mfma_f32_16x16x32_bf16 v[88:91], v[154:157], v[194:197], v[88:91]
	v_mfma_f32_16x16x32_bf16 v[80:83], v[146:149], v[202:205], v[80:83]
	v_mfma_f32_16x16x32_bf16 v[72:75], v[154:157], v[202:205], v[72:75]
	s_setprio 0
	s_setprio 1
	v_mfma_f32_16x16x32_bf16 v[116:119], v[158:161], v[174:177], v[116:119]
	v_mfma_f32_16x16x32_bf16 v[108:111], v[166:169], v[174:177], v[108:111]
	v_mfma_f32_16x16x32_bf16 v[100:103], v[158:161], v[182:185], v[100:103]
	v_mfma_f32_16x16x32_bf16 v[92:95], v[166:169], v[182:185], v[92:95]
	v_mfma_f32_16x16x32_bf16 v[84:87], v[158:161], v[190:193], v[84:87]
	v_mfma_f32_16x16x32_bf16 v[76:79], v[166:169], v[190:193], v[76:79]
	v_mfma_f32_16x16x32_bf16 v[68:71], v[158:161], v[198:201], v[68:71]
	v_mfma_f32_16x16x32_bf16 v[64:67], v[166:169], v[198:201], v[64:67]
	v_mfma_f32_16x16x32_bf16 v[116:119], v[162:165], v[178:181], v[116:119]
	v_mfma_f32_16x16x32_bf16 v[108:111], v[170:173], v[178:181], v[108:111]
	v_mfma_f32_16x16x32_bf16 v[100:103], v[162:165], v[186:189], v[100:103]
	v_mfma_f32_16x16x32_bf16 v[92:95], v[170:173], v[186:189], v[92:95]
	v_mfma_f32_16x16x32_bf16 v[84:87], v[162:165], v[194:197], v[84:87]
	v_mfma_f32_16x16x32_bf16 v[76:79], v[170:173], v[194:197], v[76:79]
	v_mfma_f32_16x16x32_bf16 v[68:71], v[162:165], v[202:205], v[68:71]
	v_mfma_f32_16x16x32_bf16 v[64:67], v[170:173], v[202:205], v[64:67]
	s_setprio 0
	s_barrier
	s_add_i32 s26, s51, s36
	v_lshl_add_u64 v[142:143], v[142:143], 0, s[94:95]
	s_mov_b32 m0, s26
	ds_read_b128 v[174:177], v145 offset:49152
	ds_read_b128 v[178:181], v145 offset:50176
	ds_read_b128 v[182:185], v145 offset:51200
	ds_read_b128 v[186:189], v145 offset:52224
	ds_read_b128 v[190:193], v145 offset:53248
	ds_read_b128 v[194:197], v145 offset:54272
	ds_read_b128 v[198:201], v145 offset:55296
	ds_read_b128 v[202:205], v145 offset:56320
	global_load_lds_dwordx4 v[142:143], off
	s_add_i32 m0, s26, 0x2000
	s_add_u32 s24, s24, 0x40080
	v_lshl_add_u64 v[142:143], v[206:207], 0, s[94:95]
	s_addc_u32 s25, s25, 0
	s_add_i32 s26, s52, s36
	global_load_lds_dwordx4 v[142:143], off
	v_lshl_add_u64 v[142:143], s[24:25], 0, v[232:233]
	s_mov_b32 m0, s26
	s_nop 0
	global_load_lds_dwordx4 v[142:143], off
	v_lshl_add_u64 v[142:143], s[24:25], 0, v[132:133]
	s_add_i32 m0, s26, 0x2000
	s_nop 0
	global_load_lds_dwordx4 v[142:143], off
	v_lshl_add_u64 v[142:143], v[208:209], 0, s[94:95]
	s_mov_b32 m0, s43
	s_nop 0
	global_load_lds_dwordx4 v[142:143], off
	v_lshl_add_u64 v[142:143], v[210:211], 0, s[94:95]
	s_mov_b32 m0, s44
	s_nop 0
	global_load_lds_dwordx4 v[142:143], off
	s_waitcnt vmcnt(8)
	s_waitcnt lgkmcnt(0)
	s_barrier
	s_setprio 1
	s_waitcnt lgkmcnt(0)
	v_mfma_f32_16x16x32_bf16 v[60:63], v[138:141], v[174:177], v[60:63]
	v_mfma_f32_16x16x32_bf16 v[56:59], v[150:153], v[174:177], v[56:59]
	v_mfma_f32_16x16x32_bf16 v[48:51], v[138:141], v[182:185], v[48:51]
	v_mfma_f32_16x16x32_bf16 v[40:43], v[150:153], v[182:185], v[40:43]
	v_mfma_f32_16x16x32_bf16 v[32:35], v[138:141], v[190:193], v[32:35]
	v_mfma_f32_16x16x32_bf16 v[24:27], v[150:153], v[190:193], v[24:27]
	v_mfma_f32_16x16x32_bf16 v[16:19], v[138:141], v[198:201], v[16:19]
	v_mfma_f32_16x16x32_bf16 v[8:11], v[150:153], v[198:201], v[8:11]
	v_mfma_f32_16x16x32_bf16 v[60:63], v[146:149], v[178:181], v[60:63]
	v_mfma_f32_16x16x32_bf16 v[56:59], v[154:157], v[178:181], v[56:59]
	v_mfma_f32_16x16x32_bf16 v[48:51], v[146:149], v[186:189], v[48:51]
	v_mfma_f32_16x16x32_bf16 v[40:43], v[154:157], v[186:189], v[40:43]
	v_mfma_f32_16x16x32_bf16 v[32:35], v[146:149], v[194:197], v[32:35]
	v_mfma_f32_16x16x32_bf16 v[24:27], v[154:157], v[194:197], v[24:27]
	v_mfma_f32_16x16x32_bf16 v[16:19], v[146:149], v[202:205], v[16:19]
	v_mfma_f32_16x16x32_bf16 v[8:11], v[154:157], v[202:205], v[8:11]
	s_setprio 0
	s_setprio 1
	v_mfma_f32_16x16x32_bf16 v[52:55], v[158:161], v[174:177], v[52:55]
	v_mfma_f32_16x16x32_bf16 v[44:47], v[166:169], v[174:177], v[44:47]
	v_mfma_f32_16x16x32_bf16 v[36:39], v[158:161], v[182:185], v[36:39]
	v_mfma_f32_16x16x32_bf16 v[28:31], v[166:169], v[182:185], v[28:31]
	v_mfma_f32_16x16x32_bf16 v[20:23], v[158:161], v[190:193], v[20:23]
	v_mfma_f32_16x16x32_bf16 v[12:15], v[166:169], v[190:193], v[12:15]
	v_mfma_f32_16x16x32_bf16 v[4:7], v[158:161], v[198:201], v[4:7]
	v_mfma_f32_16x16x32_bf16 v[0:3], v[166:169], v[198:201], v[0:3]
	v_mfma_f32_16x16x32_bf16 v[52:55], v[162:165], v[178:181], v[52:55]
	v_mfma_f32_16x16x32_bf16 v[44:47], v[170:173], v[178:181], v[44:47]
	v_mfma_f32_16x16x32_bf16 v[36:39], v[162:165], v[186:189], v[36:39]
	v_mfma_f32_16x16x32_bf16 v[28:31], v[170:173], v[186:189], v[28:31]
	v_mfma_f32_16x16x32_bf16 v[20:23], v[162:165], v[194:197], v[20:23]
	v_mfma_f32_16x16x32_bf16 v[12:15], v[170:173], v[194:197], v[12:15]
	v_mfma_f32_16x16x32_bf16 v[4:7], v[162:165], v[202:205], v[4:7]
	v_mfma_f32_16x16x32_bf16 v[0:3], v[170:173], v[202:205], v[0:3]
	s_setprio 0
	s_barrier
	s_add_i32 s50, s50, 2
	s_add_u32 s48, s48, 0x100
	s_addc_u32 s49, s49, 0
	s_add_u32 s22, s22, 0x100
	s_addc_u32 s23, s23, 0
	s_cmp_gt_u32 s50, 13
	s_cbranch_scc0 .LBB0_188
	s_and_b64 vcc, exec, s[10:11]
	s_cbranch_vccz .LBB0_191
	s_barrier

.LBB0_911:
	s_ashr_i32 s15, s14, 31
	s_lshl_b64 s[16:17], s[14:15], 19
	s_add_u32 s16, s30, s16
	s_addc_u32 s17, s31, s17
	s_and_b64 s[18:19], s[2:3], exec
	s_cselect_b32 s5, s17, s25
	s_cselect_b32 s15, s16, s24
	s_ashr_i32 s13, s12, 31
	s_lshl_b64 s[18:19], s[12:13], 19
	s_add_u32 s18, s34, s18
	s_addc_u32 s19, s35, s19
	s_and_b64 s[26:27], s[2:3], exec
	s_cselect_b32 s13, s19, s23
	s_cselect_b32 s21, s18, s22
	s_add_u32 s48, s22, 0x100
	s_addc_u32 s49, s23, 0
	s_add_u32 s22, s24, 0x40080
	s_addc_u32 s23, s25, 0
	s_mov_b32 s50, -2
	s_add_u32 s24, s22, 0xfffc0080
	s_addc_u32 s25, s23, -1
	s_add_i32 s51, 0, 0x10000
	s_cmp_eq_u32 s50, 12
	s_cselect_b32 s27, s5, s25
	s_cselect_b32 s26, s15, s24
	v_add_u32_e32 v142, s51, v144
	s_cselect_b32 s25, s13, s49
	s_cselect_b32 s24, s21, s48
	s_add_i32 s54, 0, 0x14000
	ds_read_b128 v[138:141], v142
	ds_read_b128 v[146:149], v142 offset:1024
	ds_read_b128 v[150:153], v142 offset:2048
	ds_read_b128 v[154:157], v142 offset:3072
	v_add_u32_e32 v142, s54, v144
	ds_read_b128 v[158:161], v142
	ds_read_b128 v[162:165], v142 offset:1024
	ds_read_b128 v[166:169], v142 offset:2048
	ds_read_b128 v[170:173], v142 offset:3072
	v_lshl_add_u64 v[142:143], s[22:23], 0, v[136:137]
	s_add_i32 m0, s37, 0xc000
	ds_read_b128 v[174:177], v145
	ds_read_b128 v[178:181], v145 offset:1024
	ds_read_b128 v[182:185], v145 offset:2048
	ds_read_b128 v[186:189], v145 offset:3072
	ds_read_b128 v[190:193], v145 offset:4096
	ds_read_b128 v[194:197], v145 offset:5120
	ds_read_b128 v[198:201], v145 offset:6144
	ds_read_b128 v[202:205], v145 offset:7168
	global_load_lds_dwordx4 v[142:143], off
	v_lshl_add_u64 v[142:143], s[22:23], 0, v[134:135]
	s_add_i32 m0, s37, 0xe000
	s_nop 0
	global_load_lds_dwordx4 v[142:143], off
	s_waitcnt vmcnt(8)
	s_waitcnt lgkmcnt(0)
	s_barrier
	s_setprio 1
	s_waitcnt lgkmcnt(0)
	v_mfma_f32_16x16x32_bf16 v[124:127], v[138:141], v[174:177], 0
	v_mfma_f32_16x16x32_bf16 v[120:123], v[150:153], v[174:177], 0
	v_mfma_f32_16x16x32_bf16 v[108:111], v[138:141], v[182:185], 0
	v_mfma_f32_16x16x32_bf16 v[104:107], v[150:153], v[182:185], 0
	v_mfma_f32_16x16x32_bf16 v[92:95], v[138:141], v[190:193], 0
	v_mfma_f32_16x16x32_bf16 v[88:91], v[150:153], v[190:193], 0
	v_mfma_f32_16x16x32_bf16 v[76:79], v[138:141], v[198:201], 0
	v_mfma_f32_16x16x32_bf16 v[72:75], v[150:153], v[198:201], 0
	v_mfma_f32_16x16x32_bf16 v[124:127], v[146:149], v[178:181], v[124:127]
	v_mfma_f32_16x16x32_bf16 v[120:123], v[154:157], v[178:181], v[120:123]
	v_mfma_f32_16x16x32_bf16 v[108:111], v[146:149], v[186:189], v[108:111]
	v_mfma_f32_16x16x32_bf16 v[104:107], v[154:157], v[186:189], v[104:107]
	v_mfma_f32_16x16x32_bf16 v[92:95], v[146:149], v[194:197], v[92:95]
	v_mfma_f32_16x16x32_bf16 v[88:91], v[154:157], v[194:197], v[88:91]
	v_mfma_f32_16x16x32_bf16 v[76:79], v[146:149], v[202:205], v[76:79]
	v_mfma_f32_16x16x32_bf16 v[72:75], v[154:157], v[202:205], v[72:75]
	s_setprio 0
	s_setprio 1
	v_mfma_f32_16x16x32_bf16 v[116:119], v[158:161], v[174:177], 0
	v_mfma_f32_16x16x32_bf16 v[112:115], v[166:169], v[174:177], 0
	v_mfma_f32_16x16x32_bf16 v[100:103], v[158:161], v[182:185], 0
	v_mfma_f32_16x16x32_bf16 v[96:99], v[166:169], v[182:185], 0
	v_mfma_f32_16x16x32_bf16 v[84:87], v[158:161], v[190:193], 0
	v_mfma_f32_16x16x32_bf16 v[80:83], v[166:169], v[190:193], 0
	v_mfma_f32_16x16x32_bf16 v[68:71], v[158:161], v[198:201], 0
	v_mfma_f32_16x16x32_bf16 v[64:67], v[166:169], v[198:201], 0
	v_mfma_f32_16x16x32_bf16 v[116:119], v[162:165], v[178:181], v[116:119]
	v_mfma_f32_16x16x32_bf16 v[112:115], v[170:173], v[178:181], v[112:115]
	v_mfma_f32_16x16x32_bf16 v[100:103], v[162:165], v[186:189], v[100:103]
	v_mfma_f32_16x16x32_bf16 v[96:99], v[170:173], v[186:189], v[96:99]
	v_mfma_f32_16x16x32_bf16 v[84:87], v[162:165], v[194:197], v[84:87]
	v_mfma_f32_16x16x32_bf16 v[80:83], v[170:173], v[194:197], v[80:83]
	v_mfma_f32_16x16x32_bf16 v[68:71], v[162:165], v[202:205], v[68:71]
	v_mfma_f32_16x16x32_bf16 v[64:67], v[170:173], v[202:205], v[64:67]
	s_setprio 0
	s_barrier
	s_add_i32 s51, s51, s36
	v_lshl_add_u64 v[142:143], s[24:25], 0, v[232:233]
	s_mov_b32 m0, s51
	ds_read_b128 v[174:177], v145 offset:16384
	ds_read_b128 v[178:181], v145 offset:17408
	ds_read_b128 v[182:185], v145 offset:18432
	ds_read_b128 v[186:189], v145 offset:19456
	ds_read_b128 v[190:193], v145 offset:20480
	ds_read_b128 v[194:197], v145 offset:21504
	ds_read_b128 v[198:201], v145 offset:22528
	ds_read_b128 v[202:205], v145 offset:23552
	global_load_lds_dwordx4 v[142:143], off
	s_add_i32 m0, s51, 0x2000
	s_add_u32 s52, s24, 0x40000
	v_lshl_add_u64 v[206:207], s[24:25], 0, v[132:133]
	s_addc_u32 s53, s25, 0
	s_add_i32 s51, s54, s36
	global_load_lds_dwordx4 v[206:207], off
	v_lshl_add_u64 v[208:209], s[52:53], 0, v[232:233]
	s_mov_b32 m0, s51
	v_lshl_add_u64 v[210:211], s[26:27], 0, v[130:131]
	global_load_lds_dwordx4 v[208:209], off
	v_lshl_add_u64 v[208:209], s[52:53], 0, v[132:133]
	s_add_i32 m0, s51, 0x2000
	s_nop 0
	global_load_lds_dwordx4 v[208:209], off
	v_lshl_add_u64 v[208:209], s[26:27], 0, v[128:129]
	s_waitcnt vmcnt(6)
	s_waitcnt lgkmcnt(0)
	s_barrier
	s_setprio 1
	s_waitcnt lgkmcnt(0)
	v_mfma_f32_16x16x32_bf16 v[60:63], v[138:141], v[174:177], 0
	v_mfma_f32_16x16x32_bf16 v[56:59], v[150:153], v[174:177], 0
	v_mfma_f32_16x16x32_bf16 v[44:47], v[138:141], v[182:185], 0
	v_mfma_f32_16x16x32_bf16 v[40:43], v[150:153], v[182:185], 0
	v_mfma_f32_16x16x32_bf16 v[28:31], v[138:141], v[190:193], 0
	v_mfma_f32_16x16x32_bf16 v[24:27], v[150:153], v[190:193], 0
	v_mfma_f32_16x16x32_bf16 v[12:15], v[138:141], v[198:201], 0
	v_mfma_f32_16x16x32_bf16 v[8:11], v[150:153], v[198:201], 0
	v_mfma_f32_16x16x32_bf16 v[60:63], v[146:149], v[178:181], v[60:63]
	v_mfma_f32_16x16x32_bf16 v[56:59], v[154:157], v[178:181], v[56:59]
	v_mfma_f32_16x16x32_bf16 v[44:47], v[146:149], v[186:189], v[44:47]
	v_mfma_f32_16x16x32_bf16 v[40:43], v[154:157], v[186:189], v[40:43]
	v_mfma_f32_16x16x32_bf16 v[28:31], v[146:149], v[194:197], v[28:31]
	v_mfma_f32_16x16x32_bf16 v[24:27], v[154:157], v[194:197], v[24:27]
	v_mfma_f32_16x16x32_bf16 v[12:15], v[146:149], v[202:205], v[12:15]
	v_mfma_f32_16x16x32_bf16 v[8:11], v[154:157], v[202:205], v[8:11]
	s_setprio 0
	s_setprio 1
	v_mfma_f32_16x16x32_bf16 v[52:55], v[158:161], v[174:177], 0
	v_mfma_f32_16x16x32_bf16 v[48:51], v[166:169], v[174:177], 0
	v_mfma_f32_16x16x32_bf16 v[36:39], v[158:161], v[182:185], 0
	v_mfma_f32_16x16x32_bf16 v[32:35], v[166:169], v[182:185], 0
	v_mfma_f32_16x16x32_bf16 v[20:23], v[158:161], v[190:193], 0
	v_mfma_f32_16x16x32_bf16 v[16:19], v[166:169], v[190:193], 0
	v_mfma_f32_16x16x32_bf16 v[4:7], v[158:161], v[198:201], 0
	v_mfma_f32_16x16x32_bf16 v[0:3], v[166:169], v[198:201], 0
	v_mfma_f32_16x16x32_bf16 v[52:55], v[162:165], v[178:181], v[52:55]
	v_mfma_f32_16x16x32_bf16 v[48:51], v[170:173], v[178:181], v[48:51]
	v_mfma_f32_16x16x32_bf16 v[36:39], v[162:165], v[186:189], v[36:39]
	v_mfma_f32_16x16x32_bf16 v[32:35], v[170:173], v[186:189], v[32:35]
	v_mfma_f32_16x16x32_bf16 v[20:23], v[162:165], v[194:197], v[20:23]
	v_mfma_f32_16x16x32_bf16 v[16:19], v[170:173], v[194:197], v[16:19]
	v_mfma_f32_16x16x32_bf16 v[4:7], v[162:165], v[202:205], v[4:7]
	v_mfma_f32_16x16x32_bf16 v[0:3], v[170:173], v[202:205], v[0:3]
	s_setprio 0
	s_barrier
	s_branch .Lzmid_2

.Lzmid_2:
	s_add_i32 s51, 0, 0x18000
	s_add_i32 s52, 0, 0x1c000
	v_add_u32_e32 v154, s51, v144
	v_add_u32_e32 v170, s52, v144
	ds_read_b128 v[138:141], v154
	ds_read_b128 v[146:149], v154 offset:1024
	ds_read_b128 v[150:153], v154 offset:2048
	ds_read_b128 v[154:157], v154 offset:3072
	ds_read_b128 v[158:161], v170
	ds_read_b128 v[162:165], v170 offset:1024
	ds_read_b128 v[166:169], v170 offset:2048
	ds_read_b128 v[170:173], v170 offset:3072
	s_add_u32 s26, s26, 0x40000
	s_addc_u32 s27, s27, 0
	s_mov_b32 m0, s37
	s_nop 0
	global_load_lds_dwordx4 v[208:209], off
	s_mov_b32 m0, s38
	s_nop 0
	global_load_lds_dwordx4 v[210:211], off
	s_mov_b32 m0, s39
	v_lshl_add_u64 v[212:213], s[26:27], 0, v[128:129]
	ds_read_b128 v[174:177], v145 offset:32768
	ds_read_b128 v[178:181], v145 offset:33792
	ds_read_b128 v[182:185], v145 offset:34816
	ds_read_b128 v[186:189], v145 offset:35840
	ds_read_b128 v[190:193], v145 offset:36864
	ds_read_b128 v[194:197], v145 offset:37888
	ds_read_b128 v[198:201], v145 offset:38912
	ds_read_b128 v[202:205], v145 offset:39936
	global_load_lds_dwordx4 v[212:213], off
	v_lshl_add_u64 v[212:213], s[26:27], 0, v[130:131]
	s_mov_b32 m0, s40
	s_nop 0
	global_load_lds_dwordx4 v[212:213], off
	s_waitcnt vmcnt(8)
	s_waitcnt lgkmcnt(0)
	s_barrier
	s_setprio 1
	s_waitcnt lgkmcnt(0)
	v_mfma_f32_16x16x32_bf16 v[124:127], v[138:141], v[174:177], v[124:127]
	v_mfma_f32_16x16x32_bf16 v[120:123], v[150:153], v[174:177], v[120:123]
	v_mfma_f32_16x16x32_bf16 v[108:111], v[138:141], v[182:185], v[108:111]
	v_mfma_f32_16x16x32_bf16 v[104:107], v[150:153], v[182:185], v[104:107]
	v_mfma_f32_16x16x32_bf16 v[92:95], v[138:141], v[190:193], v[92:95]
	v_mfma_f32_16x16x32_bf16 v[88:91], v[150:153], v[190:193], v[88:91]
	v_mfma_f32_16x16x32_bf16 v[76:79], v[138:141], v[198:201], v[76:79]
	v_mfma_f32_16x16x32_bf16 v[72:75], v[150:153], v[198:201], v[72:75]
	v_mfma_f32_16x16x32_bf16 v[124:127], v[146:149], v[178:181], v[124:127]
	v_mfma_f32_16x16x32_bf16 v[120:123], v[154:157], v[178:181], v[120:123]
	v_mfma_f32_16x16x32_bf16 v[108:111], v[146:149], v[186:189], v[108:111]
	v_mfma_f32_16x16x32_bf16 v[104:107], v[154:157], v[186:189], v[104:107]
	v_mfma_f32_16x16x32_bf16 v[92:95], v[146:149], v[194:197], v[92:95]
	v_mfma_f32_16x16x32_bf16 v[88:91], v[154:157], v[194:197], v[88:91]
	v_mfma_f32_16x16x32_bf16 v[76:79], v[146:149], v[202:205], v[76:79]
	v_mfma_f32_16x16x32_bf16 v[72:75], v[154:157], v[202:205], v[72:75]
	s_setprio 0
	s_setprio 1
	v_mfma_f32_16x16x32_bf16 v[116:119], v[158:161], v[174:177], v[116:119]
	v_mfma_f32_16x16x32_bf16 v[112:115], v[166:169], v[174:177], v[112:115]
	v_mfma_f32_16x16x32_bf16 v[100:103], v[158:161], v[182:185], v[100:103]
	v_mfma_f32_16x16x32_bf16 v[96:99], v[166:169], v[182:185], v[96:99]
	v_mfma_f32_16x16x32_bf16 v[84:87], v[158:161], v[190:193], v[84:87]
	v_mfma_f32_16x16x32_bf16 v[80:83], v[166:169], v[190:193], v[80:83]
	v_mfma_f32_16x16x32_bf16 v[68:71], v[158:161], v[198:201], v[68:71]
	v_mfma_f32_16x16x32_bf16 v[64:67], v[166:169], v[198:201], v[64:67]
	v_mfma_f32_16x16x32_bf16 v[116:119], v[162:165], v[178:181], v[116:119]
	v_mfma_f32_16x16x32_bf16 v[112:115], v[170:173], v[178:181], v[112:115]
	v_mfma_f32_16x16x32_bf16 v[100:103], v[162:165], v[186:189], v[100:103]
	v_mfma_f32_16x16x32_bf16 v[96:99], v[170:173], v[186:189], v[96:99]
	v_mfma_f32_16x16x32_bf16 v[84:87], v[162:165], v[194:197], v[84:87]
	v_mfma_f32_16x16x32_bf16 v[80:83], v[170:173], v[194:197], v[80:83]
	v_mfma_f32_16x16x32_bf16 v[68:71], v[162:165], v[202:205], v[68:71]
	v_mfma_f32_16x16x32_bf16 v[64:67], v[170:173], v[202:205], v[64:67]
	s_setprio 0
	s_barrier
	s_add_i32 s26, s51, s36
	v_lshl_add_u64 v[142:143], v[142:143], 0, s[94:95]
	s_mov_b32 m0, s26
	ds_read_b128 v[174:177], v145 offset:49152
	ds_read_b128 v[178:181], v145 offset:50176
	ds_read_b128 v[182:185], v145 offset:51200
	ds_read_b128 v[186:189], v145 offset:52224
	ds_read_b128 v[190:193], v145 offset:53248
	ds_read_b128 v[194:197], v145 offset:54272
	ds_read_b128 v[198:201], v145 offset:55296
	ds_read_b128 v[202:205], v145 offset:56320
	global_load_lds_dwordx4 v[142:143], off
	s_add_i32 m0, s26, 0x2000
	s_add_u32 s24, s24, 0x40080
	v_lshl_add_u64 v[142:143], v[206:207], 0, s[94:95]
	s_addc_u32 s25, s25, 0
	s_add_i32 s26, s52, s36
	global_load_lds_dwordx4 v[142:143], off
	v_lshl_add_u64 v[142:143], s[24:25], 0, v[232:233]
	s_mov_b32 m0, s26
	s_nop 0
	global_load_lds_dwordx4 v[142:143], off
	v_lshl_add_u64 v[142:143], s[24:25], 0, v[132:133]
	s_add_i32 m0, s26, 0x2000
	s_nop 0
	global_load_lds_dwordx4 v[142:143], off
	v_lshl_add_u64 v[142:143], v[208:209], 0, s[94:95]
	s_mov_b32 m0, s43
	s_nop 0
	global_load_lds_dwordx4 v[142:143], off
	v_lshl_add_u64 v[142:143], v[210:211], 0, s[94:95]
	s_mov_b32 m0, s44
	s_nop 0
	global_load_lds_dwordx4 v[142:143], off
	s_waitcnt vmcnt(8)
	s_waitcnt lgkmcnt(0)
	s_barrier
	s_setprio 1
	s_waitcnt lgkmcnt(0)
	v_mfma_f32_16x16x32_bf16 v[60:63], v[138:141], v[174:177], v[60:63]
	v_mfma_f32_16x16x32_bf16 v[56:59], v[150:153], v[174:177], v[56:59]
	v_mfma_f32_16x16x32_bf16 v[44:47], v[138:141], v[182:185], v[44:47]
	v_mfma_f32_16x16x32_bf16 v[40:43], v[150:153], v[182:185], v[40:43]
	v_mfma_f32_16x16x32_bf16 v[28:31], v[138:141], v[190:193], v[28:31]
	v_mfma_f32_16x16x32_bf16 v[24:27], v[150:153], v[190:193], v[24:27]
	v_mfma_f32_16x16x32_bf16 v[12:15], v[138:141], v[198:201], v[12:15]
	v_mfma_f32_16x16x32_bf16 v[8:11], v[150:153], v[198:201], v[8:11]
	v_mfma_f32_16x16x32_bf16 v[60:63], v[146:149], v[178:181], v[60:63]
	v_mfma_f32_16x16x32_bf16 v[56:59], v[154:157], v[178:181], v[56:59]
	v_mfma_f32_16x16x32_bf16 v[44:47], v[146:149], v[186:189], v[44:47]
	v_mfma_f32_16x16x32_bf16 v[40:43], v[154:157], v[186:189], v[40:43]
	v_mfma_f32_16x16x32_bf16 v[28:31], v[146:149], v[194:197], v[28:31]
	v_mfma_f32_16x16x32_bf16 v[24:27], v[154:157], v[194:197], v[24:27]
	v_mfma_f32_16x16x32_bf16 v[12:15], v[146:149], v[202:205], v[12:15]
	v_mfma_f32_16x16x32_bf16 v[8:11], v[154:157], v[202:205], v[8:11]
	s_setprio 0
	s_setprio 1
	v_mfma_f32_16x16x32_bf16 v[52:55], v[158:161], v[174:177], v[52:55]
	v_mfma_f32_16x16x32_bf16 v[48:51], v[166:169], v[174:177], v[48:51]
	v_mfma_f32_16x16x32_bf16 v[36:39], v[158:161], v[182:185], v[36:39]
	v_mfma_f32_16x16x32_bf16 v[32:35], v[166:169], v[182:185], v[32:35]
	v_mfma_f32_16x16x32_bf16 v[20:23], v[158:161], v[190:193], v[20:23]
	v_mfma_f32_16x16x32_bf16 v[16:19], v[166:169], v[190:193], v[16:19]
	v_mfma_f32_16x16x32_bf16 v[4:7], v[158:161], v[198:201], v[4:7]
	v_mfma_f32_16x16x32_bf16 v[0:3], v[166:169], v[198:201], v[0:3]
	v_mfma_f32_16x16x32_bf16 v[52:55], v[162:165], v[178:181], v[52:55]
	v_mfma_f32_16x16x32_bf16 v[48:51], v[170:173], v[178:181], v[48:51]
	v_mfma_f32_16x16x32_bf16 v[36:39], v[162:165], v[186:189], v[36:39]
	v_mfma_f32_16x16x32_bf16 v[32:35], v[170:173], v[186:189], v[32:35]
	v_mfma_f32_16x16x32_bf16 v[20:23], v[162:165], v[194:197], v[20:23]
	v_mfma_f32_16x16x32_bf16 v[16:19], v[170:173], v[194:197], v[16:19]
	v_mfma_f32_16x16x32_bf16 v[4:7], v[162:165], v[202:205], v[4:7]
	v_mfma_f32_16x16x32_bf16 v[0:3], v[170:173], v[202:205], v[0:3]
	s_setprio 0
	s_barrier
	s_add_i32 s50, s50, 2
	s_add_u32 s48, s48, 0x100
	s_addc_u32 s49, s49, 0
	s_add_u32 s22, s22, 0x100
	s_addc_u32 s23, s23, 0
	s_cmp_gt_u32 s50, 13
	s_cbranch_scc0 .LBB0_912
	s_and_b64 vcc, exec, s[10:11]
	s_cbranch_vccz .LBB0_915
	s_barrier

.LBB0_1163:
	s_ashr_i32 s23, s22, 31
	s_lshl_b64 s[24:25], s[22:23], 19
	s_add_u32 s24, s42, s24
	s_addc_u32 s25, s43, s25
	s_and_b64 s[26:27], s[4:5], exec
	s_cselect_b32 s23, s25, s35
	s_cselect_b32 s56, s24, s34
	s_ashr_i32 s21, s20, 31
	s_lshl_b64 s[26:27], s[20:21], 19
	s_add_u32 s26, s44, s26
	s_addc_u32 s27, s45, s27
	s_and_b64 s[36:37], s[4:5], exec
	s_cselect_b32 s21, s27, s31
	s_cselect_b32 s57, s26, s30
	s_add_u32 s58, s30, 0x100
	s_addc_u32 s59, s31, 0
	s_add_u32 s30, s34, 0x40080
	s_addc_u32 s31, s35, 0
	s_mov_b32 s60, -2
	s_waitcnt vmcnt(0)
	s_add_u32 s34, s30, 0xfffc0080
	s_addc_u32 s35, s31, -1
	s_add_i32 s61, 0, 0x10000
	s_cmp_eq_u32 s60, 12
	s_cselect_b32 s37, s23, s35
	s_cselect_b32 s36, s56, s34
	s_cselect_b32 s35, s21, s59
	s_cselect_b32 s34, s57, s58
	s_add_i32 s64, 0, 0x14000
	v_add_u32_e32 v140, s61, v174
	v_add_u32_e32 v166, s64, v174
	ds_read_b128 v[128:131], v140
	ds_read_b128 v[132:135], v140 offset:1024
	ds_read_b128 v[136:139], v140 offset:2048
	ds_read_b128 v[140:143], v140 offset:3072
	ds_read_b128 v[154:157], v166
	ds_read_b128 v[158:161], v166 offset:1024
	ds_read_b128 v[162:165], v166 offset:2048
	ds_read_b128 v[166:169], v166 offset:3072
	v_lshl_add_u64 v[204:205], s[30:31], 0, v[152:153]
	s_add_i32 m0, s29, 0xc000
	ds_read_b128 v[170:173], v175
	ds_read_b128 v[176:179], v175 offset:1024
	ds_read_b128 v[180:183], v175 offset:2048
	ds_read_b128 v[184:187], v175 offset:3072
	ds_read_b128 v[188:191], v175 offset:4096
	ds_read_b128 v[192:195], v175 offset:5120
	ds_read_b128 v[196:199], v175 offset:6144
	ds_read_b128 v[200:203], v175 offset:7168
	global_load_lds_dwordx4 v[204:205], off
	v_lshl_add_u64 v[204:205], s[30:31], 0, v[150:151]
	s_add_i32 m0, s29, 0xe000
	s_nop 0
	global_load_lds_dwordx4 v[204:205], off
	s_waitcnt vmcnt(8)
	s_waitcnt lgkmcnt(0)
	s_barrier
	s_setprio 1
	s_waitcnt lgkmcnt(0)
	v_mfma_f32_16x16x32_bf16 v[124:127], v[128:131], v[170:173], 0
	v_mfma_f32_16x16x32_bf16 v[120:123], v[136:139], v[170:173], 0
	v_mfma_f32_16x16x32_bf16 v[108:111], v[128:131], v[180:183], 0
	v_mfma_f32_16x16x32_bf16 v[104:107], v[136:139], v[180:183], 0
	v_mfma_f32_16x16x32_bf16 v[92:95], v[128:131], v[188:191], 0
	v_mfma_f32_16x16x32_bf16 v[88:91], v[136:139], v[188:191], 0
	v_mfma_f32_16x16x32_bf16 v[80:83], v[128:131], v[196:199], 0
	v_mfma_f32_16x16x32_bf16 v[72:75], v[136:139], v[196:199], 0
	v_mfma_f32_16x16x32_bf16 v[124:127], v[132:135], v[176:179], v[124:127]
	v_mfma_f32_16x16x32_bf16 v[120:123], v[140:143], v[176:179], v[120:123]
	v_mfma_f32_16x16x32_bf16 v[108:111], v[132:135], v[184:187], v[108:111]
	v_mfma_f32_16x16x32_bf16 v[104:107], v[140:143], v[184:187], v[104:107]
	v_mfma_f32_16x16x32_bf16 v[92:95], v[132:135], v[192:195], v[92:95]
	v_mfma_f32_16x16x32_bf16 v[88:91], v[140:143], v[192:195], v[88:91]
	v_mfma_f32_16x16x32_bf16 v[80:83], v[132:135], v[200:203], v[80:83]
	v_mfma_f32_16x16x32_bf16 v[72:75], v[140:143], v[200:203], v[72:75]
	s_setprio 0
	s_setprio 1
	v_mfma_f32_16x16x32_bf16 v[116:119], v[154:157], v[170:173], 0
	v_mfma_f32_16x16x32_bf16 v[112:115], v[162:165], v[170:173], 0
	v_mfma_f32_16x16x32_bf16 v[100:103], v[154:157], v[180:183], 0
	v_mfma_f32_16x16x32_bf16 v[96:99], v[162:165], v[180:183], 0
	v_mfma_f32_16x16x32_bf16 v[84:87], v[154:157], v[188:191], 0
	v_mfma_f32_16x16x32_bf16 v[76:79], v[162:165], v[188:191], 0
	v_mfma_f32_16x16x32_bf16 v[68:71], v[154:157], v[196:199], 0
	v_mfma_f32_16x16x32_bf16 v[64:67], v[162:165], v[196:199], 0
	v_mfma_f32_16x16x32_bf16 v[116:119], v[158:161], v[176:179], v[116:119]
	v_mfma_f32_16x16x32_bf16 v[112:115], v[166:169], v[176:179], v[112:115]
	v_mfma_f32_16x16x32_bf16 v[100:103], v[158:161], v[184:187], v[100:103]
	v_mfma_f32_16x16x32_bf16 v[96:99], v[166:169], v[184:187], v[96:99]
	v_mfma_f32_16x16x32_bf16 v[84:87], v[158:161], v[192:195], v[84:87]
	v_mfma_f32_16x16x32_bf16 v[76:79], v[166:169], v[192:195], v[76:79]
	v_mfma_f32_16x16x32_bf16 v[68:71], v[158:161], v[200:203], v[68:71]
	v_mfma_f32_16x16x32_bf16 v[64:67], v[166:169], v[200:203], v[64:67]
	s_setprio 0
	s_barrier
	s_add_i32 s61, s61, s41
	v_lshl_add_u64 v[204:205], s[34:35], 0, v[232:233]
	s_mov_b32 m0, s61
	ds_read_b128 v[170:173], v175 offset:16384
	ds_read_b128 v[176:179], v175 offset:17408
	ds_read_b128 v[180:183], v175 offset:18432
	ds_read_b128 v[184:187], v175 offset:19456
	ds_read_b128 v[188:191], v175 offset:20480
	ds_read_b128 v[192:195], v175 offset:21504
	ds_read_b128 v[196:199], v175 offset:22528
	ds_read_b128 v[200:203], v175 offset:23552
	global_load_lds_dwordx4 v[204:205], off
	s_add_i32 m0, s61, 0x2000
	s_add_u32 s62, s34, 0x40000
	v_lshl_add_u64 v[206:207], s[34:35], 0, v[148:149]
	s_addc_u32 s63, s35, 0
	s_add_i32 s61, s64, s41
	global_load_lds_dwordx4 v[206:207], off
	v_lshl_add_u64 v[208:209], s[62:63], 0, v[232:233]
	s_mov_b32 m0, s61
	v_lshl_add_u64 v[210:211], s[36:37], 0, v[146:147]
	global_load_lds_dwordx4 v[208:209], off
	v_lshl_add_u64 v[208:209], s[62:63], 0, v[148:149]
	s_add_i32 m0, s61, 0x2000
	s_nop 0
	global_load_lds_dwordx4 v[208:209], off
	v_lshl_add_u64 v[208:209], s[36:37], 0, v[144:145]
	s_waitcnt vmcnt(6)
	s_waitcnt lgkmcnt(0)
	s_barrier
	s_setprio 1
	s_waitcnt lgkmcnt(0)
	v_mfma_f32_16x16x32_bf16 v[60:63], v[128:131], v[170:173], 0
	v_mfma_f32_16x16x32_bf16 v[56:59], v[136:139], v[170:173], 0
	v_mfma_f32_16x16x32_bf16 v[48:51], v[128:131], v[180:183], 0
	v_mfma_f32_16x16x32_bf16 v[40:43], v[136:139], v[180:183], 0
	v_mfma_f32_16x16x32_bf16 v[28:31], v[128:131], v[188:191], 0
	v_mfma_f32_16x16x32_bf16 v[24:27], v[136:139], v[188:191], 0
	v_mfma_f32_16x16x32_bf16 v[16:19], v[128:131], v[196:199], 0
	v_mfma_f32_16x16x32_bf16 v[8:11], v[136:139], v[196:199], 0
	v_mfma_f32_16x16x32_bf16 v[60:63], v[132:135], v[176:179], v[60:63]
	v_mfma_f32_16x16x32_bf16 v[56:59], v[140:143], v[176:179], v[56:59]
	v_mfma_f32_16x16x32_bf16 v[48:51], v[132:135], v[184:187], v[48:51]
	v_mfma_f32_16x16x32_bf16 v[40:43], v[140:143], v[184:187], v[40:43]
	v_mfma_f32_16x16x32_bf16 v[28:31], v[132:135], v[192:195], v[28:31]
	v_mfma_f32_16x16x32_bf16 v[24:27], v[140:143], v[192:195], v[24:27]
	v_mfma_f32_16x16x32_bf16 v[16:19], v[132:135], v[200:203], v[16:19]
	v_mfma_f32_16x16x32_bf16 v[8:11], v[140:143], v[200:203], v[8:11]
	s_setprio 0
	s_setprio 1
	v_mfma_f32_16x16x32_bf16 v[52:55], v[154:157], v[170:173], 0
	v_mfma_f32_16x16x32_bf16 v[44:47], v[162:165], v[170:173], 0
	v_mfma_f32_16x16x32_bf16 v[36:39], v[154:157], v[180:183], 0
	v_mfma_f32_16x16x32_bf16 v[32:35], v[162:165], v[180:183], 0
	v_mfma_f32_16x16x32_bf16 v[20:23], v[154:157], v[188:191], 0
	v_mfma_f32_16x16x32_bf16 v[12:15], v[162:165], v[188:191], 0
	v_mfma_f32_16x16x32_bf16 v[4:7], v[154:157], v[196:199], 0
	v_mfma_f32_16x16x32_bf16 v[0:3], v[162:165], v[196:199], 0
	v_mfma_f32_16x16x32_bf16 v[52:55], v[158:161], v[176:179], v[52:55]
	v_mfma_f32_16x16x32_bf16 v[44:47], v[166:169], v[176:179], v[44:47]
	v_mfma_f32_16x16x32_bf16 v[36:39], v[158:161], v[184:187], v[36:39]
	v_mfma_f32_16x16x32_bf16 v[32:35], v[166:169], v[184:187], v[32:35]
	v_mfma_f32_16x16x32_bf16 v[20:23], v[158:161], v[192:195], v[20:23]
	v_mfma_f32_16x16x32_bf16 v[12:15], v[166:169], v[192:195], v[12:15]
	v_mfma_f32_16x16x32_bf16 v[4:7], v[158:161], v[200:203], v[4:7]
	v_mfma_f32_16x16x32_bf16 v[0:3], v[166:169], v[200:203], v[0:3]
	s_setprio 0
	s_barrier
	s_branch .Lzmid_3

.Lzmid_3:
	s_add_i32 s61, 0, 0x18000
	s_add_i32 s62, 0, 0x1c000
	v_add_u32_e32 v140, s61, v174
	v_add_u32_e32 v166, s62, v174
	ds_read_b128 v[128:131], v140
	ds_read_b128 v[132:135], v140 offset:1024
	ds_read_b128 v[136:139], v140 offset:2048
	ds_read_b128 v[140:143], v140 offset:3072
	ds_read_b128 v[154:157], v166
	ds_read_b128 v[158:161], v166 offset:1024
	ds_read_b128 v[162:165], v166 offset:2048
	ds_read_b128 v[166:169], v166 offset:3072
	s_add_u32 s36, s36, 0x40000
	s_addc_u32 s37, s37, 0
	s_mov_b32 m0, s29
	s_nop 0
	global_load_lds_dwordx4 v[208:209], off
	s_mov_b32 m0, s46
	s_nop 0
	global_load_lds_dwordx4 v[210:211], off
	s_mov_b32 m0, s47
	v_lshl_add_u64 v[212:213], s[36:37], 0, v[144:145]
	ds_read_b128 v[170:173], v175 offset:32768
	ds_read_b128 v[176:179], v175 offset:33792
	ds_read_b128 v[180:183], v175 offset:34816
	ds_read_b128 v[184:187], v175 offset:35840
	ds_read_b128 v[188:191], v175 offset:36864
	ds_read_b128 v[192:195], v175 offset:37888
	ds_read_b128 v[196:199], v175 offset:38912
	ds_read_b128 v[200:203], v175 offset:39936
	global_load_lds_dwordx4 v[212:213], off
	v_lshl_add_u64 v[212:213], s[36:37], 0, v[146:147]
	s_mov_b32 m0, s48
	s_nop 0
	global_load_lds_dwordx4 v[212:213], off
	s_waitcnt vmcnt(8)
	s_waitcnt lgkmcnt(0)
	s_barrier
	s_setprio 1
	s_waitcnt lgkmcnt(0)
	v_mfma_f32_16x16x32_bf16 v[124:127], v[128:131], v[170:173], v[124:127]
	v_mfma_f32_16x16x32_bf16 v[120:123], v[136:139], v[170:173], v[120:123]
	v_mfma_f32_16x16x32_bf16 v[108:111], v[128:131], v[180:183], v[108:111]
	v_mfma_f32_16x16x32_bf16 v[104:107], v[136:139], v[180:183], v[104:107]
	v_mfma_f32_16x16x32_bf16 v[92:95], v[128:131], v[188:191], v[92:95]
	v_mfma_f32_16x16x32_bf16 v[88:91], v[136:139], v[188:191], v[88:91]
	v_mfma_f32_16x16x32_bf16 v[80:83], v[128:131], v[196:199], v[80:83]
	v_mfma_f32_16x16x32_bf16 v[72:75], v[136:139], v[196:199], v[72:75]
	v_mfma_f32_16x16x32_bf16 v[124:127], v[132:135], v[176:179], v[124:127]
	v_mfma_f32_16x16x32_bf16 v[120:123], v[140:143], v[176:179], v[120:123]
	v_mfma_f32_16x16x32_bf16 v[108:111], v[132:135], v[184:187], v[108:111]
	v_mfma_f32_16x16x32_bf16 v[104:107], v[140:143], v[184:187], v[104:107]
	v_mfma_f32_16x16x32_bf16 v[92:95], v[132:135], v[192:195], v[92:95]
	v_mfma_f32_16x16x32_bf16 v[88:91], v[140:143], v[192:195], v[88:91]
	v_mfma_f32_16x16x32_bf16 v[80:83], v[132:135], v[200:203], v[80:83]
	v_mfma_f32_16x16x32_bf16 v[72:75], v[140:143], v[200:203], v[72:75]
	s_setprio 0
	s_setprio 1
	v_mfma_f32_16x16x32_bf16 v[116:119], v[154:157], v[170:173], v[116:119]
	v_mfma_f32_16x16x32_bf16 v[112:115], v[162:165], v[170:173], v[112:115]
	v_mfma_f32_16x16x32_bf16 v[100:103], v[154:157], v[180:183], v[100:103]
	v_mfma_f32_16x16x32_bf16 v[96:99], v[162:165], v[180:183], v[96:99]
	v_mfma_f32_16x16x32_bf16 v[84:87], v[154:157], v[188:191], v[84:87]
	v_mfma_f32_16x16x32_bf16 v[76:79], v[162:165], v[188:191], v[76:79]
	v_mfma_f32_16x16x32_bf16 v[68:71], v[154:157], v[196:199], v[68:71]
	v_mfma_f32_16x16x32_bf16 v[64:67], v[162:165], v[196:199], v[64:67]
	v_mfma_f32_16x16x32_bf16 v[116:119], v[158:161], v[176:179], v[116:119]
	v_mfma_f32_16x16x32_bf16 v[112:115], v[166:169], v[176:179], v[112:115]
	v_mfma_f32_16x16x32_bf16 v[100:103], v[158:161], v[184:187], v[100:103]
	v_mfma_f32_16x16x32_bf16 v[96:99], v[166:169], v[184:187], v[96:99]
	v_mfma_f32_16x16x32_bf16 v[84:87], v[158:161], v[192:195], v[84:87]
	v_mfma_f32_16x16x32_bf16 v[76:79], v[166:169], v[192:195], v[76:79]
	v_mfma_f32_16x16x32_bf16 v[68:71], v[158:161], v[200:203], v[68:71]
	v_mfma_f32_16x16x32_bf16 v[64:67], v[166:169], v[200:203], v[64:67]
	s_setprio 0
	s_barrier
	s_add_i32 s36, s61, s41
	v_lshl_add_u64 v[204:205], v[204:205], 0, s[94:95]
	s_mov_b32 m0, s36
	ds_read_b128 v[170:173], v175 offset:49152
	ds_read_b128 v[176:179], v175 offset:50176
	ds_read_b128 v[180:183], v175 offset:51200
	ds_read_b128 v[184:187], v175 offset:52224
	ds_read_b128 v[188:191], v175 offset:53248
	ds_read_b128 v[192:195], v175 offset:54272
	ds_read_b128 v[196:199], v175 offset:55296
	ds_read_b128 v[200:203], v175 offset:56320
	global_load_lds_dwordx4 v[204:205], off
	s_add_i32 m0, s36, 0x2000
	s_add_u32 s34, s34, 0x40080
	v_lshl_add_u64 v[204:205], v[206:207], 0, s[94:95]
	s_addc_u32 s35, s35, 0
	s_add_i32 s36, s62, s41
	global_load_lds_dwordx4 v[204:205], off
	v_lshl_add_u64 v[204:205], s[34:35], 0, v[232:233]
	s_mov_b32 m0, s36
	s_nop 0
	global_load_lds_dwordx4 v[204:205], off
	v_lshl_add_u64 v[204:205], s[34:35], 0, v[148:149]
	s_add_i32 m0, s36, 0x2000
	s_nop 0
	global_load_lds_dwordx4 v[204:205], off
	v_lshl_add_u64 v[204:205], v[208:209], 0, s[94:95]
	s_mov_b32 m0, s51
	s_nop 0
	global_load_lds_dwordx4 v[204:205], off
	v_lshl_add_u64 v[204:205], v[210:211], 0, s[94:95]
	s_mov_b32 m0, s52
	s_nop 0
	global_load_lds_dwordx4 v[204:205], off
	s_waitcnt vmcnt(8)
	s_waitcnt lgkmcnt(0)
	s_barrier
	s_setprio 1
	s_waitcnt lgkmcnt(0)
	v_mfma_f32_16x16x32_bf16 v[60:63], v[128:131], v[170:173], v[60:63]
	v_mfma_f32_16x16x32_bf16 v[56:59], v[136:139], v[170:173], v[56:59]
	v_mfma_f32_16x16x32_bf16 v[48:51], v[128:131], v[180:183], v[48:51]
	v_mfma_f32_16x16x32_bf16 v[40:43], v[136:139], v[180:183], v[40:43]
	v_mfma_f32_16x16x32_bf16 v[28:31], v[128:131], v[188:191], v[28:31]
	v_mfma_f32_16x16x32_bf16 v[24:27], v[136:139], v[188:191], v[24:27]
	v_mfma_f32_16x16x32_bf16 v[16:19], v[128:131], v[196:199], v[16:19]
	v_mfma_f32_16x16x32_bf16 v[8:11], v[136:139], v[196:199], v[8:11]
	v_mfma_f32_16x16x32_bf16 v[60:63], v[132:135], v[176:179], v[60:63]
	v_mfma_f32_16x16x32_bf16 v[56:59], v[140:143], v[176:179], v[56:59]
	v_mfma_f32_16x16x32_bf16 v[48:51], v[132:135], v[184:187], v[48:51]
	v_mfma_f32_16x16x32_bf16 v[40:43], v[140:143], v[184:187], v[40:43]
	v_mfma_f32_16x16x32_bf16 v[28:31], v[132:135], v[192:195], v[28:31]
	v_mfma_f32_16x16x32_bf16 v[24:27], v[140:143], v[192:195], v[24:27]
	v_mfma_f32_16x16x32_bf16 v[16:19], v[132:135], v[200:203], v[16:19]
	v_mfma_f32_16x16x32_bf16 v[8:11], v[140:143], v[200:203], v[8:11]
	s_setprio 0
	s_setprio 1
	v_mfma_f32_16x16x32_bf16 v[52:55], v[154:157], v[170:173], v[52:55]
	v_mfma_f32_16x16x32_bf16 v[44:47], v[162:165], v[170:173], v[44:47]
	v_mfma_f32_16x16x32_bf16 v[36:39], v[154:157], v[180:183], v[36:39]
	v_mfma_f32_16x16x32_bf16 v[32:35], v[162:165], v[180:183], v[32:35]
	v_mfma_f32_16x16x32_bf16 v[20:23], v[154:157], v[188:191], v[20:23]
	v_mfma_f32_16x16x32_bf16 v[12:15], v[162:165], v[188:191], v[12:15]
	v_mfma_f32_16x16x32_bf16 v[4:7], v[154:157], v[196:199], v[4:7]
	v_mfma_f32_16x16x32_bf16 v[0:3], v[162:165], v[196:199], v[0:3]
	v_mfma_f32_16x16x32_bf16 v[52:55], v[158:161], v[176:179], v[52:55]
	v_mfma_f32_16x16x32_bf16 v[44:47], v[166:169], v[176:179], v[44:47]
	v_mfma_f32_16x16x32_bf16 v[36:39], v[158:161], v[184:187], v[36:39]
	v_mfma_f32_16x16x32_bf16 v[32:35], v[166:169], v[184:187], v[32:35]
	v_mfma_f32_16x16x32_bf16 v[20:23], v[158:161], v[192:195], v[20:23]
	v_mfma_f32_16x16x32_bf16 v[12:15], v[166:169], v[192:195], v[12:15]
	v_mfma_f32_16x16x32_bf16 v[4:7], v[158:161], v[200:203], v[4:7]
	v_mfma_f32_16x16x32_bf16 v[0:3], v[166:169], v[200:203], v[0:3]
	s_setprio 0
	s_barrier
	s_add_i32 s60, s60, 2
	s_add_u32 s58, s58, 0x100
	s_addc_u32 s59, s59, 0
	s_add_u32 s30, s30, 0x100
	s_addc_u32 s31, s31, 0
	s_cmp_gt_u32 s60, 13
	s_cbranch_scc0 .LBB0_1164
	s_and_b64 vcc, exec, s[18:19]
	s_cbranch_vccz .LBB0_1167
	s_barrier

.LBB0_1306:
	s_ashr_i32 s17, s16, 31
	s_lshl_b64 s[18:19], s[16:17], 19
	s_add_u32 s18, s34, s18
	s_addc_u32 s19, s35, s19
	s_and_b64 s[20:21], s[4:5], exec
	s_cselect_b32 s7, s19, s27
	s_cselect_b32 s17, s18, s26
	s_ashr_i32 s15, s14, 31
	s_lshl_b64 s[20:21], s[14:15], 19
	s_add_u32 s20, s36, s20
	s_addc_u32 s21, s37, s21
	s_and_b64 s[28:29], s[4:5], exec
	s_cselect_b32 s15, s21, s25
	s_cselect_b32 s23, s20, s24
	s_add_u32 s50, s24, 0x100
	s_addc_u32 s51, s25, 0
	s_add_u32 s24, s26, 0x40080
	s_addc_u32 s25, s27, 0
	s_mov_b32 s52, -2
	s_add_u32 s26, s24, 0xfffc0080
	s_addc_u32 s27, s25, -1
	s_add_i32 s53, 0, 0x10000
	s_cmp_eq_u32 s52, 12
	s_cselect_b32 s29, s7, s27
	s_cselect_b32 s28, s17, s26
	v_add_u32_e32 v142, s53, v144
	s_cselect_b32 s27, s15, s51
	s_cselect_b32 s26, s23, s50
	s_add_i32 s56, 0, 0x14000
	ds_read_b128 v[138:141], v142
	ds_read_b128 v[146:149], v142 offset:1024
	ds_read_b128 v[150:153], v142 offset:2048
	ds_read_b128 v[154:157], v142 offset:3072
	v_add_u32_e32 v142, s56, v144
	ds_read_b128 v[158:161], v142
	ds_read_b128 v[162:165], v142 offset:1024
	ds_read_b128 v[166:169], v142 offset:2048
	ds_read_b128 v[170:173], v142 offset:3072
	v_lshl_add_u64 v[142:143], s[24:25], 0, v[136:137]
	s_add_i32 m0, s39, 0xc000
	ds_read_b128 v[174:177], v145
	ds_read_b128 v[178:181], v145 offset:1024
	ds_read_b128 v[182:185], v145 offset:2048
	ds_read_b128 v[186:189], v145 offset:3072
	ds_read_b128 v[190:193], v145 offset:4096
	ds_read_b128 v[194:197], v145 offset:5120
	ds_read_b128 v[198:201], v145 offset:6144
	ds_read_b128 v[202:205], v145 offset:7168
	global_load_lds_dwordx4 v[142:143], off
	v_lshl_add_u64 v[142:143], s[24:25], 0, v[134:135]
	s_add_i32 m0, s39, 0xe000
	s_nop 0
	global_load_lds_dwordx4 v[142:143], off
	s_waitcnt vmcnt(8)
	s_waitcnt lgkmcnt(0)
	s_barrier
	s_setprio 1
	s_waitcnt lgkmcnt(0)
	v_mfma_f32_16x16x32_bf16 v[124:127], v[138:141], v[174:177], 0
	v_mfma_f32_16x16x32_bf16 v[120:123], v[150:153], v[174:177], 0
	v_mfma_f32_16x16x32_bf16 v[108:111], v[138:141], v[182:185], 0
	v_mfma_f32_16x16x32_bf16 v[104:107], v[150:153], v[182:185], 0
	v_mfma_f32_16x16x32_bf16 v[92:95], v[138:141], v[190:193], 0
	v_mfma_f32_16x16x32_bf16 v[88:91], v[150:153], v[190:193], 0
	v_mfma_f32_16x16x32_bf16 v[76:79], v[138:141], v[198:201], 0
	v_mfma_f32_16x16x32_bf16 v[72:75], v[150:153], v[198:201], 0
	v_mfma_f32_16x16x32_bf16 v[124:127], v[146:149], v[178:181], v[124:127]
	v_mfma_f32_16x16x32_bf16 v[120:123], v[154:157], v[178:181], v[120:123]
	v_mfma_f32_16x16x32_bf16 v[108:111], v[146:149], v[186:189], v[108:111]
	v_mfma_f32_16x16x32_bf16 v[104:107], v[154:157], v[186:189], v[104:107]
	v_mfma_f32_16x16x32_bf16 v[92:95], v[146:149], v[194:197], v[92:95]
	v_mfma_f32_16x16x32_bf16 v[88:91], v[154:157], v[194:197], v[88:91]
	v_mfma_f32_16x16x32_bf16 v[76:79], v[146:149], v[202:205], v[76:79]
	v_mfma_f32_16x16x32_bf16 v[72:75], v[154:157], v[202:205], v[72:75]
	s_setprio 0
	s_setprio 1
	v_mfma_f32_16x16x32_bf16 v[116:119], v[158:161], v[174:177], 0
	v_mfma_f32_16x16x32_bf16 v[112:115], v[166:169], v[174:177], 0
	v_mfma_f32_16x16x32_bf16 v[100:103], v[158:161], v[182:185], 0
	v_mfma_f32_16x16x32_bf16 v[96:99], v[166:169], v[182:185], 0
	v_mfma_f32_16x16x32_bf16 v[84:87], v[158:161], v[190:193], 0
	v_mfma_f32_16x16x32_bf16 v[80:83], v[166:169], v[190:193], 0
	v_mfma_f32_16x16x32_bf16 v[68:71], v[158:161], v[198:201], 0
	v_mfma_f32_16x16x32_bf16 v[64:67], v[166:169], v[198:201], 0
	v_mfma_f32_16x16x32_bf16 v[116:119], v[162:165], v[178:181], v[116:119]
	v_mfma_f32_16x16x32_bf16 v[112:115], v[170:173], v[178:181], v[112:115]
	v_mfma_f32_16x16x32_bf16 v[100:103], v[162:165], v[186:189], v[100:103]
	v_mfma_f32_16x16x32_bf16 v[96:99], v[170:173], v[186:189], v[96:99]
	v_mfma_f32_16x16x32_bf16 v[84:87], v[162:165], v[194:197], v[84:87]
	v_mfma_f32_16x16x32_bf16 v[80:83], v[170:173], v[194:197], v[80:83]
	v_mfma_f32_16x16x32_bf16 v[68:71], v[162:165], v[202:205], v[68:71]
	v_mfma_f32_16x16x32_bf16 v[64:67], v[170:173], v[202:205], v[64:67]
	s_setprio 0
	s_barrier
	s_add_i32 s53, s53, s38
	v_lshl_add_u64 v[142:143], s[26:27], 0, v[232:233]
	s_mov_b32 m0, s53
	ds_read_b128 v[174:177], v145 offset:16384
	ds_read_b128 v[178:181], v145 offset:17408
	ds_read_b128 v[182:185], v145 offset:18432
	ds_read_b128 v[186:189], v145 offset:19456
	ds_read_b128 v[190:193], v145 offset:20480
	ds_read_b128 v[194:197], v145 offset:21504
	ds_read_b128 v[198:201], v145 offset:22528
	ds_read_b128 v[202:205], v145 offset:23552
	global_load_lds_dwordx4 v[142:143], off
	s_add_i32 m0, s53, 0x2000
	s_add_u32 s54, s26, 0x40000
	v_lshl_add_u64 v[206:207], s[26:27], 0, v[132:133]
	s_addc_u32 s55, s27, 0
	s_add_i32 s53, s56, s38
	global_load_lds_dwordx4 v[206:207], off
	v_lshl_add_u64 v[208:209], s[54:55], 0, v[232:233]
	s_mov_b32 m0, s53
	v_lshl_add_u64 v[210:211], s[28:29], 0, v[130:131]
	global_load_lds_dwordx4 v[208:209], off
	v_lshl_add_u64 v[208:209], s[54:55], 0, v[132:133]
	s_add_i32 m0, s53, 0x2000
	s_nop 0
	global_load_lds_dwordx4 v[208:209], off
	v_lshl_add_u64 v[208:209], s[28:29], 0, v[128:129]
	s_waitcnt vmcnt(6)
	s_waitcnt lgkmcnt(0)
	s_barrier
	s_setprio 1
	s_waitcnt lgkmcnt(0)
	v_mfma_f32_16x16x32_bf16 v[60:63], v[138:141], v[174:177], 0
	v_mfma_f32_16x16x32_bf16 v[56:59], v[150:153], v[174:177], 0
	v_mfma_f32_16x16x32_bf16 v[44:47], v[138:141], v[182:185], 0
	v_mfma_f32_16x16x32_bf16 v[40:43], v[150:153], v[182:185], 0
	v_mfma_f32_16x16x32_bf16 v[28:31], v[138:141], v[190:193], 0
	v_mfma_f32_16x16x32_bf16 v[24:27], v[150:153], v[190:193], 0
	v_mfma_f32_16x16x32_bf16 v[12:15], v[138:141], v[198:201], 0
	v_mfma_f32_16x16x32_bf16 v[8:11], v[150:153], v[198:201], 0
	v_mfma_f32_16x16x32_bf16 v[60:63], v[146:149], v[178:181], v[60:63]
	v_mfma_f32_16x16x32_bf16 v[56:59], v[154:157], v[178:181], v[56:59]
	v_mfma_f32_16x16x32_bf16 v[44:47], v[146:149], v[186:189], v[44:47]
	v_mfma_f32_16x16x32_bf16 v[40:43], v[154:157], v[186:189], v[40:43]
	v_mfma_f32_16x16x32_bf16 v[28:31], v[146:149], v[194:197], v[28:31]
	v_mfma_f32_16x16x32_bf16 v[24:27], v[154:157], v[194:197], v[24:27]
	v_mfma_f32_16x16x32_bf16 v[12:15], v[146:149], v[202:205], v[12:15]
	v_mfma_f32_16x16x32_bf16 v[8:11], v[154:157], v[202:205], v[8:11]
	s_setprio 0
	s_setprio 1
	v_mfma_f32_16x16x32_bf16 v[52:55], v[158:161], v[174:177], 0
	v_mfma_f32_16x16x32_bf16 v[48:51], v[166:169], v[174:177], 0
	v_mfma_f32_16x16x32_bf16 v[36:39], v[158:161], v[182:185], 0
	v_mfma_f32_16x16x32_bf16 v[32:35], v[166:169], v[182:185], 0
	v_mfma_f32_16x16x32_bf16 v[20:23], v[158:161], v[190:193], 0
	v_mfma_f32_16x16x32_bf16 v[16:19], v[166:169], v[190:193], 0
	v_mfma_f32_16x16x32_bf16 v[4:7], v[158:161], v[198:201], 0
	v_mfma_f32_16x16x32_bf16 v[0:3], v[166:169], v[198:201], 0
	v_mfma_f32_16x16x32_bf16 v[52:55], v[162:165], v[178:181], v[52:55]
	v_mfma_f32_16x16x32_bf16 v[48:51], v[170:173], v[178:181], v[48:51]
	v_mfma_f32_16x16x32_bf16 v[36:39], v[162:165], v[186:189], v[36:39]
	v_mfma_f32_16x16x32_bf16 v[32:35], v[170:173], v[186:189], v[32:35]
	v_mfma_f32_16x16x32_bf16 v[20:23], v[162:165], v[194:197], v[20:23]
	v_mfma_f32_16x16x32_bf16 v[16:19], v[170:173], v[194:197], v[16:19]
	v_mfma_f32_16x16x32_bf16 v[4:7], v[162:165], v[202:205], v[4:7]
	v_mfma_f32_16x16x32_bf16 v[0:3], v[170:173], v[202:205], v[0:3]
	s_setprio 0
	s_barrier
	s_branch .Lzmid_4

.Lzmid_4:
	s_add_i32 s53, 0, 0x18000
	s_add_i32 s54, 0, 0x1c000
	v_add_u32_e32 v154, s53, v144
	v_add_u32_e32 v170, s54, v144
	ds_read_b128 v[138:141], v154
	ds_read_b128 v[146:149], v154 offset:1024
	ds_read_b128 v[150:153], v154 offset:2048
	ds_read_b128 v[154:157], v154 offset:3072
	ds_read_b128 v[158:161], v170
	ds_read_b128 v[162:165], v170 offset:1024
	ds_read_b128 v[166:169], v170 offset:2048
	ds_read_b128 v[170:173], v170 offset:3072
	s_add_u32 s28, s28, 0x40000
	s_addc_u32 s29, s29, 0
	s_mov_b32 m0, s39
	s_nop 0
	global_load_lds_dwordx4 v[208:209], off
	s_mov_b32 m0, s40
	s_nop 0
	global_load_lds_dwordx4 v[210:211], off
	s_mov_b32 m0, s41
	v_lshl_add_u64 v[212:213], s[28:29], 0, v[128:129]
	ds_read_b128 v[174:177], v145 offset:32768
	ds_read_b128 v[178:181], v145 offset:33792
	ds_read_b128 v[182:185], v145 offset:34816
	ds_read_b128 v[186:189], v145 offset:35840
	ds_read_b128 v[190:193], v145 offset:36864
	ds_read_b128 v[194:197], v145 offset:37888
	ds_read_b128 v[198:201], v145 offset:38912
	ds_read_b128 v[202:205], v145 offset:39936
	global_load_lds_dwordx4 v[212:213], off
	v_lshl_add_u64 v[212:213], s[28:29], 0, v[130:131]
	s_mov_b32 m0, s42
	s_nop 0
	global_load_lds_dwordx4 v[212:213], off
	s_waitcnt vmcnt(8)
	s_waitcnt lgkmcnt(0)
	s_barrier
	s_setprio 1
	s_waitcnt lgkmcnt(0)
	v_mfma_f32_16x16x32_bf16 v[124:127], v[138:141], v[174:177], v[124:127]
	v_mfma_f32_16x16x32_bf16 v[120:123], v[150:153], v[174:177], v[120:123]
	v_mfma_f32_16x16x32_bf16 v[108:111], v[138:141], v[182:185], v[108:111]
	v_mfma_f32_16x16x32_bf16 v[104:107], v[150:153], v[182:185], v[104:107]
	v_mfma_f32_16x16x32_bf16 v[92:95], v[138:141], v[190:193], v[92:95]
	v_mfma_f32_16x16x32_bf16 v[88:91], v[150:153], v[190:193], v[88:91]
	v_mfma_f32_16x16x32_bf16 v[76:79], v[138:141], v[198:201], v[76:79]
	v_mfma_f32_16x16x32_bf16 v[72:75], v[150:153], v[198:201], v[72:75]
	v_mfma_f32_16x16x32_bf16 v[124:127], v[146:149], v[178:181], v[124:127]
	v_mfma_f32_16x16x32_bf16 v[120:123], v[154:157], v[178:181], v[120:123]
	v_mfma_f32_16x16x32_bf16 v[108:111], v[146:149], v[186:189], v[108:111]
	v_mfma_f32_16x16x32_bf16 v[104:107], v[154:157], v[186:189], v[104:107]
	v_mfma_f32_16x16x32_bf16 v[92:95], v[146:149], v[194:197], v[92:95]
	v_mfma_f32_16x16x32_bf16 v[88:91], v[154:157], v[194:197], v[88:91]
	v_mfma_f32_16x16x32_bf16 v[76:79], v[146:149], v[202:205], v[76:79]
	v_mfma_f32_16x16x32_bf16 v[72:75], v[154:157], v[202:205], v[72:75]
	s_setprio 0
	s_setprio 1
	v_mfma_f32_16x16x32_bf16 v[116:119], v[158:161], v[174:177], v[116:119]
	v_mfma_f32_16x16x32_bf16 v[112:115], v[166:169], v[174:177], v[112:115]
	v_mfma_f32_16x16x32_bf16 v[100:103], v[158:161], v[182:185], v[100:103]
	v_mfma_f32_16x16x32_bf16 v[96:99], v[166:169], v[182:185], v[96:99]
	v_mfma_f32_16x16x32_bf16 v[84:87], v[158:161], v[190:193], v[84:87]
	v_mfma_f32_16x16x32_bf16 v[80:83], v[166:169], v[190:193], v[80:83]
	v_mfma_f32_16x16x32_bf16 v[68:71], v[158:161], v[198:201], v[68:71]
	v_mfma_f32_16x16x32_bf16 v[64:67], v[166:169], v[198:201], v[64:67]
	v_mfma_f32_16x16x32_bf16 v[116:119], v[162:165], v[178:181], v[116:119]
	v_mfma_f32_16x16x32_bf16 v[112:115], v[170:173], v[178:181], v[112:115]
	v_mfma_f32_16x16x32_bf16 v[100:103], v[162:165], v[186:189], v[100:103]
	v_mfma_f32_16x16x32_bf16 v[96:99], v[170:173], v[186:189], v[96:99]
	v_mfma_f32_16x16x32_bf16 v[84:87], v[162:165], v[194:197], v[84:87]
	v_mfma_f32_16x16x32_bf16 v[80:83], v[170:173], v[194:197], v[80:83]
	v_mfma_f32_16x16x32_bf16 v[68:71], v[162:165], v[202:205], v[68:71]
	v_mfma_f32_16x16x32_bf16 v[64:67], v[170:173], v[202:205], v[64:67]
	s_setprio 0
	s_barrier
	s_add_i32 s28, s53, s38
	v_lshl_add_u64 v[142:143], v[142:143], 0, s[94:95]
	s_mov_b32 m0, s28
	ds_read_b128 v[174:177], v145 offset:49152
	ds_read_b128 v[178:181], v145 offset:50176
	ds_read_b128 v[182:185], v145 offset:51200
	ds_read_b128 v[186:189], v145 offset:52224
	ds_read_b128 v[190:193], v145 offset:53248
	ds_read_b128 v[194:197], v145 offset:54272
	ds_read_b128 v[198:201], v145 offset:55296
	ds_read_b128 v[202:205], v145 offset:56320
	global_load_lds_dwordx4 v[142:143], off
	s_add_i32 m0, s28, 0x2000
	s_add_u32 s26, s26, 0x40080
	v_lshl_add_u64 v[142:143], v[206:207], 0, s[94:95]
	s_addc_u32 s27, s27, 0
	s_add_i32 s28, s54, s38
	global_load_lds_dwordx4 v[142:143], off
	v_lshl_add_u64 v[142:143], s[26:27], 0, v[232:233]
	s_mov_b32 m0, s28
	s_nop 0
	global_load_lds_dwordx4 v[142:143], off
	v_lshl_add_u64 v[142:143], s[26:27], 0, v[132:133]
	s_add_i32 m0, s28, 0x2000
	s_nop 0
	global_load_lds_dwordx4 v[142:143], off
	v_lshl_add_u64 v[142:143], v[208:209], 0, s[94:95]
	s_mov_b32 m0, s45
	s_nop 0
	global_load_lds_dwordx4 v[142:143], off
	v_lshl_add_u64 v[142:143], v[210:211], 0, s[94:95]
	s_mov_b32 m0, s46
	s_nop 0
	global_load_lds_dwordx4 v[142:143], off
	s_waitcnt vmcnt(8)
	s_waitcnt lgkmcnt(0)
	s_barrier
	s_setprio 1
	s_waitcnt lgkmcnt(0)
	v_mfma_f32_16x16x32_bf16 v[60:63], v[138:141], v[174:177], v[60:63]
	v_mfma_f32_16x16x32_bf16 v[56:59], v[150:153], v[174:177], v[56:59]
	v_mfma_f32_16x16x32_bf16 v[44:47], v[138:141], v[182:185], v[44:47]
	v_mfma_f32_16x16x32_bf16 v[40:43], v[150:153], v[182:185], v[40:43]
	v_mfma_f32_16x16x32_bf16 v[28:31], v[138:141], v[190:193], v[28:31]
	v_mfma_f32_16x16x32_bf16 v[24:27], v[150:153], v[190:193], v[24:27]
	v_mfma_f32_16x16x32_bf16 v[12:15], v[138:141], v[198:201], v[12:15]
	v_mfma_f32_16x16x32_bf16 v[8:11], v[150:153], v[198:201], v[8:11]
	v_mfma_f32_16x16x32_bf16 v[60:63], v[146:149], v[178:181], v[60:63]
	v_mfma_f32_16x16x32_bf16 v[56:59], v[154:157], v[178:181], v[56:59]
	v_mfma_f32_16x16x32_bf16 v[44:47], v[146:149], v[186:189], v[44:47]
	v_mfma_f32_16x16x32_bf16 v[40:43], v[154:157], v[186:189], v[40:43]
	v_mfma_f32_16x16x32_bf16 v[28:31], v[146:149], v[194:197], v[28:31]
	v_mfma_f32_16x16x32_bf16 v[24:27], v[154:157], v[194:197], v[24:27]
	v_mfma_f32_16x16x32_bf16 v[12:15], v[146:149], v[202:205], v[12:15]
	v_mfma_f32_16x16x32_bf16 v[8:11], v[154:157], v[202:205], v[8:11]
	s_setprio 0
	s_setprio 1
	v_mfma_f32_16x16x32_bf16 v[52:55], v[158:161], v[174:177], v[52:55]
	v_mfma_f32_16x16x32_bf16 v[48:51], v[166:169], v[174:177], v[48:51]
	v_mfma_f32_16x16x32_bf16 v[36:39], v[158:161], v[182:185], v[36:39]
	v_mfma_f32_16x16x32_bf16 v[32:35], v[166:169], v[182:185], v[32:35]
	v_mfma_f32_16x16x32_bf16 v[20:23], v[158:161], v[190:193], v[20:23]
	v_mfma_f32_16x16x32_bf16 v[16:19], v[166:169], v[190:193], v[16:19]
	v_mfma_f32_16x16x32_bf16 v[4:7], v[158:161], v[198:201], v[4:7]
	v_mfma_f32_16x16x32_bf16 v[0:3], v[166:169], v[198:201], v[0:3]
	v_mfma_f32_16x16x32_bf16 v[52:55], v[162:165], v[178:181], v[52:55]
	v_mfma_f32_16x16x32_bf16 v[48:51], v[170:173], v[178:181], v[48:51]
	v_mfma_f32_16x16x32_bf16 v[36:39], v[162:165], v[186:189], v[36:39]
	v_mfma_f32_16x16x32_bf16 v[32:35], v[170:173], v[186:189], v[32:35]
	v_mfma_f32_16x16x32_bf16 v[20:23], v[162:165], v[194:197], v[20:23]
	v_mfma_f32_16x16x32_bf16 v[16:19], v[170:173], v[194:197], v[16:19]
	v_mfma_f32_16x16x32_bf16 v[4:7], v[162:165], v[202:205], v[4:7]
	v_mfma_f32_16x16x32_bf16 v[0:3], v[170:173], v[202:205], v[0:3]
	s_setprio 0
	s_barrier
	s_add_i32 s52, s52, 2
	s_add_u32 s50, s50, 0x100
	s_addc_u32 s51, s51, 0
	s_add_u32 s24, s24, 0x100
	s_addc_u32 s25, s25, 0
	s_cmp_gt_u32 s52, 13
	s_cbranch_scc0 .LBB0_1307
	s_and_b64 vcc, exec, s[12:13]
	s_cbranch_vccz .LBB0_1310
	s_barrier

.LBB0_1491:
	s_ashr_i32 s23, s22, 31
	s_lshl_b64 s[24:25], s[22:23], 21
	s_add_u32 s24, s70, s24
	s_addc_u32 s25, s71, s25
	s_and_b64 s[26:27], s[4:5], exec
	s_cselect_b32 s23, s25, s35
	s_cselect_b32 s56, s24, s34
	s_ashr_i32 s21, s20, 31
	s_lshl_b64 s[26:27], s[20:21], 21
	s_add_u32 s26, s72, s26
	s_addc_u32 s27, s76, s27
	s_and_b64 s[36:37], s[4:5], exec
	s_cselect_b32 s21, s27, s31
	s_cselect_b32 s57, s26, s30
	s_add_u32 s58, s30, 0x100
	s_addc_u32 s59, s31, 0
	s_add_u32 s30, s34, 0x100080
	s_addc_u32 s31, s35, 0
	s_mov_b32 s60, -2
	s_waitcnt vmcnt(0)
	s_add_u32 s34, s30, 0xfff00080
	s_addc_u32 s35, s31, -1
	s_add_i32 s61, 0, 0x10000
	s_cmp_eq_u32 s60, 60
	s_cselect_b32 s37, s23, s35
	s_cselect_b32 s36, s56, s34
	s_cselect_b32 s35, s21, s59
	s_cselect_b32 s34, s57, s58
	s_add_i32 s64, 0, 0x14000
	v_add_u32_e32 v100, s61, v220
	v_add_u32_e32 v156, s64, v220
	ds_read_b128 v[88:91], v100
	ds_read_b128 v[92:95], v100 offset:1024
	ds_read_b128 v[96:99], v100 offset:2048
	ds_read_b128 v[100:103], v100 offset:3072
	ds_read_b128 v[144:147], v156
	ds_read_b128 v[148:151], v156 offset:1024
	ds_read_b128 v[152:155], v156 offset:2048
	ds_read_b128 v[156:159], v156 offset:3072
	v_lshl_add_u64 v[202:203], s[30:31], 0, v[188:189]
	s_add_i32 m0, s78, 0xc000
	ds_read_b128 v[160:163], v221
	ds_read_b128 v[164:167], v221 offset:1024
	ds_read_b128 v[168:171], v221 offset:2048
	ds_read_b128 v[172:175], v221 offset:3072
	ds_read_b128 v[176:179], v221 offset:4096
	ds_read_b128 v[190:193], v221 offset:5120
	ds_read_b128 v[194:197], v221 offset:6144
	ds_read_b128 v[198:201], v221 offset:7168
	global_load_lds_dwordx4 v[202:203], off
	v_lshl_add_u64 v[202:203], s[30:31], 0, v[186:187]
	s_add_i32 m0, s78, 0xe000
	s_nop 0
	global_load_lds_dwordx4 v[202:203], off
	s_waitcnt vmcnt(8)
	s_waitcnt lgkmcnt(0)
	s_barrier
	s_setprio 1
	s_waitcnt lgkmcnt(0)
	v_mfma_f32_16x16x32_bf16 v[140:143], v[88:91], v[160:163], 0
	v_mfma_f32_16x16x32_bf16 v[136:139], v[96:99], v[160:163], 0
	v_mfma_f32_16x16x32_bf16 v[124:127], v[88:91], v[168:171], 0
	v_mfma_f32_16x16x32_bf16 v[120:123], v[96:99], v[168:171], 0
	v_mfma_f32_16x16x32_bf16 v[108:111], v[88:91], v[176:179], 0
	v_mfma_f32_16x16x32_bf16 v[104:107], v[96:99], v[176:179], 0
	v_mfma_f32_16x16x32_bf16 v[76:79], v[88:91], v[194:197], 0
	v_mfma_f32_16x16x32_bf16 v[72:75], v[96:99], v[194:197], 0
	v_mfma_f32_16x16x32_bf16 v[140:143], v[92:95], v[164:167], v[140:143]
	v_mfma_f32_16x16x32_bf16 v[136:139], v[100:103], v[164:167], v[136:139]
	v_mfma_f32_16x16x32_bf16 v[124:127], v[92:95], v[172:175], v[124:127]
	v_mfma_f32_16x16x32_bf16 v[120:123], v[100:103], v[172:175], v[120:123]
	v_mfma_f32_16x16x32_bf16 v[108:111], v[92:95], v[190:193], v[108:111]
	v_mfma_f32_16x16x32_bf16 v[104:107], v[100:103], v[190:193], v[104:107]
	v_mfma_f32_16x16x32_bf16 v[76:79], v[92:95], v[198:201], v[76:79]
	v_mfma_f32_16x16x32_bf16 v[72:75], v[100:103], v[198:201], v[72:75]
	s_setprio 0
	s_setprio 1
	v_mfma_f32_16x16x32_bf16 v[132:135], v[144:147], v[160:163], 0
	v_mfma_f32_16x16x32_bf16 v[128:131], v[152:155], v[160:163], 0
	v_mfma_f32_16x16x32_bf16 v[116:119], v[144:147], v[168:171], 0
	v_mfma_f32_16x16x32_bf16 v[112:115], v[152:155], v[168:171], 0
	v_mfma_f32_16x16x32_bf16 v[84:87], v[144:147], v[176:179], 0
	v_mfma_f32_16x16x32_bf16 v[80:83], v[152:155], v[176:179], 0
	v_mfma_f32_16x16x32_bf16 v[68:71], v[144:147], v[194:197], 0
	v_mfma_f32_16x16x32_bf16 v[64:67], v[152:155], v[194:197], 0
	v_mfma_f32_16x16x32_bf16 v[132:135], v[148:151], v[164:167], v[132:135]
	v_mfma_f32_16x16x32_bf16 v[128:131], v[156:159], v[164:167], v[128:131]
	v_mfma_f32_16x16x32_bf16 v[116:119], v[148:151], v[172:175], v[116:119]
	v_mfma_f32_16x16x32_bf16 v[112:115], v[156:159], v[172:175], v[112:115]
	v_mfma_f32_16x16x32_bf16 v[84:87], v[148:151], v[190:193], v[84:87]
	v_mfma_f32_16x16x32_bf16 v[80:83], v[156:159], v[190:193], v[80:83]
	v_mfma_f32_16x16x32_bf16 v[68:71], v[148:151], v[198:201], v[68:71]
	v_mfma_f32_16x16x32_bf16 v[64:67], v[156:159], v[198:201], v[64:67]
	s_setprio 0
	s_barrier
	s_add_i32 s61, s61, s77
	v_lshl_add_u64 v[202:203], s[34:35], 0, v[232:233]
	s_mov_b32 m0, s61
	ds_read_b128 v[160:163], v221 offset:16384
	ds_read_b128 v[164:167], v221 offset:17408
	ds_read_b128 v[168:171], v221 offset:18432
	ds_read_b128 v[172:175], v221 offset:19456
	ds_read_b128 v[176:179], v221 offset:20480
	ds_read_b128 v[190:193], v221 offset:21504
	ds_read_b128 v[194:197], v221 offset:22528
	ds_read_b128 v[198:201], v221 offset:23552
	global_load_lds_dwordx4 v[202:203], off
	s_add_i32 m0, s61, 0x2000
	s_add_u32 s62, s34, 0x100000
	v_lshl_add_u64 v[204:205], s[34:35], 0, v[184:185]
	s_addc_u32 s63, s35, 0
	s_add_i32 s61, s64, s77
	global_load_lds_dwordx4 v[204:205], off
	v_lshl_add_u64 v[206:207], s[62:63], 0, v[232:233]
	s_mov_b32 m0, s61
	v_lshl_add_u64 v[208:209], s[36:37], 0, v[182:183]
	global_load_lds_dwordx4 v[206:207], off
	v_lshl_add_u64 v[206:207], s[62:63], 0, v[184:185]
	s_add_i32 m0, s61, 0x2000
	s_nop 0
	global_load_lds_dwordx4 v[206:207], off
	v_lshl_add_u64 v[206:207], s[36:37], 0, v[180:181]
	s_waitcnt vmcnt(6)
	s_waitcnt lgkmcnt(0)
	s_barrier
	s_setprio 1
	s_waitcnt lgkmcnt(0)
	v_mfma_f32_16x16x32_bf16 v[60:63], v[88:91], v[160:163], 0
	v_mfma_f32_16x16x32_bf16 v[56:59], v[96:99], v[160:163], 0
	v_mfma_f32_16x16x32_bf16 v[44:47], v[88:91], v[168:171], 0
	v_mfma_f32_16x16x32_bf16 v[40:43], v[96:99], v[168:171], 0
	v_mfma_f32_16x16x32_bf16 v[28:31], v[88:91], v[176:179], 0
	v_mfma_f32_16x16x32_bf16 v[24:27], v[96:99], v[176:179], 0
	v_mfma_f32_16x16x32_bf16 v[12:15], v[88:91], v[194:197], 0
	v_mfma_f32_16x16x32_bf16 v[8:11], v[96:99], v[194:197], 0
	v_mfma_f32_16x16x32_bf16 v[60:63], v[92:95], v[164:167], v[60:63]
	v_mfma_f32_16x16x32_bf16 v[56:59], v[100:103], v[164:167], v[56:59]
	v_mfma_f32_16x16x32_bf16 v[44:47], v[92:95], v[172:175], v[44:47]
	v_mfma_f32_16x16x32_bf16 v[40:43], v[100:103], v[172:175], v[40:43]
	v_mfma_f32_16x16x32_bf16 v[28:31], v[92:95], v[190:193], v[28:31]
	v_mfma_f32_16x16x32_bf16 v[24:27], v[100:103], v[190:193], v[24:27]
	v_mfma_f32_16x16x32_bf16 v[12:15], v[92:95], v[198:201], v[12:15]
	v_mfma_f32_16x16x32_bf16 v[8:11], v[100:103], v[198:201], v[8:11]
	s_setprio 0
	s_setprio 1
	v_mfma_f32_16x16x32_bf16 v[52:55], v[144:147], v[160:163], 0
	v_mfma_f32_16x16x32_bf16 v[48:51], v[152:155], v[160:163], 0
	v_mfma_f32_16x16x32_bf16 v[36:39], v[144:147], v[168:171], 0
	v_mfma_f32_16x16x32_bf16 v[32:35], v[152:155], v[168:171], 0
	v_mfma_f32_16x16x32_bf16 v[20:23], v[144:147], v[176:179], 0
	v_mfma_f32_16x16x32_bf16 v[16:19], v[152:155], v[176:179], 0
	v_mfma_f32_16x16x32_bf16 v[4:7], v[144:147], v[194:197], 0
	v_mfma_f32_16x16x32_bf16 v[0:3], v[152:155], v[194:197], 0
	v_mfma_f32_16x16x32_bf16 v[52:55], v[148:151], v[164:167], v[52:55]
	v_mfma_f32_16x16x32_bf16 v[48:51], v[156:159], v[164:167], v[48:51]
	v_mfma_f32_16x16x32_bf16 v[36:39], v[148:151], v[172:175], v[36:39]
	v_mfma_f32_16x16x32_bf16 v[32:35], v[156:159], v[172:175], v[32:35]
	v_mfma_f32_16x16x32_bf16 v[20:23], v[148:151], v[190:193], v[20:23]
	v_mfma_f32_16x16x32_bf16 v[16:19], v[156:159], v[190:193], v[16:19]
	v_mfma_f32_16x16x32_bf16 v[4:7], v[148:151], v[198:201], v[4:7]
	v_mfma_f32_16x16x32_bf16 v[0:3], v[156:159], v[198:201], v[0:3]
	s_setprio 0
	s_barrier
	s_branch .Lzmid_6

.Lzmid_6:
	s_add_i32 s61, 0, 0x18000
	s_add_i32 s62, 0, 0x1c000
	v_add_u32_e32 v100, s61, v220
	v_add_u32_e32 v156, s62, v220
	ds_read_b128 v[88:91], v100
	ds_read_b128 v[92:95], v100 offset:1024
	ds_read_b128 v[96:99], v100 offset:2048
	ds_read_b128 v[100:103], v100 offset:3072
	ds_read_b128 v[144:147], v156
	ds_read_b128 v[148:151], v156 offset:1024
	ds_read_b128 v[152:155], v156 offset:2048
	ds_read_b128 v[156:159], v156 offset:3072
	s_add_u32 s36, s36, 0x100000
	s_addc_u32 s37, s37, 0
	s_mov_b32 m0, s78
	s_nop 0
	global_load_lds_dwordx4 v[206:207], off
	s_mov_b32 m0, s79
	s_nop 0
	global_load_lds_dwordx4 v[208:209], off
	s_mov_b32 m0, s80
	v_lshl_add_u64 v[210:211], s[36:37], 0, v[180:181]
	ds_read_b128 v[160:163], v221 offset:32768
	ds_read_b128 v[164:167], v221 offset:33792
	ds_read_b128 v[168:171], v221 offset:34816
	ds_read_b128 v[172:175], v221 offset:35840
	ds_read_b128 v[176:179], v221 offset:36864
	ds_read_b128 v[190:193], v221 offset:37888
	ds_read_b128 v[194:197], v221 offset:38912
	ds_read_b128 v[198:201], v221 offset:39936
	global_load_lds_dwordx4 v[210:211], off
	v_lshl_add_u64 v[210:211], s[36:37], 0, v[182:183]
	s_mov_b32 m0, s81
	s_nop 0
	global_load_lds_dwordx4 v[210:211], off
	s_waitcnt vmcnt(8)
	s_waitcnt lgkmcnt(0)
	s_barrier
	s_setprio 1
	s_waitcnt lgkmcnt(0)
	v_mfma_f32_16x16x32_bf16 v[140:143], v[88:91], v[160:163], v[140:143]
	v_mfma_f32_16x16x32_bf16 v[136:139], v[96:99], v[160:163], v[136:139]
	v_mfma_f32_16x16x32_bf16 v[124:127], v[88:91], v[168:171], v[124:127]
	v_mfma_f32_16x16x32_bf16 v[120:123], v[96:99], v[168:171], v[120:123]
	v_mfma_f32_16x16x32_bf16 v[108:111], v[88:91], v[176:179], v[108:111]
	v_mfma_f32_16x16x32_bf16 v[104:107], v[96:99], v[176:179], v[104:107]
	v_mfma_f32_16x16x32_bf16 v[76:79], v[88:91], v[194:197], v[76:79]
	v_mfma_f32_16x16x32_bf16 v[72:75], v[96:99], v[194:197], v[72:75]
	v_mfma_f32_16x16x32_bf16 v[140:143], v[92:95], v[164:167], v[140:143]
	v_mfma_f32_16x16x32_bf16 v[136:139], v[100:103], v[164:167], v[136:139]
	v_mfma_f32_16x16x32_bf16 v[124:127], v[92:95], v[172:175], v[124:127]
	v_mfma_f32_16x16x32_bf16 v[120:123], v[100:103], v[172:175], v[120:123]
	v_mfma_f32_16x16x32_bf16 v[108:111], v[92:95], v[190:193], v[108:111]
	v_mfma_f32_16x16x32_bf16 v[104:107], v[100:103], v[190:193], v[104:107]
	v_mfma_f32_16x16x32_bf16 v[76:79], v[92:95], v[198:201], v[76:79]
	v_mfma_f32_16x16x32_bf16 v[72:75], v[100:103], v[198:201], v[72:75]
	s_setprio 0
	s_setprio 1
	v_mfma_f32_16x16x32_bf16 v[132:135], v[144:147], v[160:163], v[132:135]
	v_mfma_f32_16x16x32_bf16 v[128:131], v[152:155], v[160:163], v[128:131]
	v_mfma_f32_16x16x32_bf16 v[116:119], v[144:147], v[168:171], v[116:119]
	v_mfma_f32_16x16x32_bf16 v[112:115], v[152:155], v[168:171], v[112:115]
	v_mfma_f32_16x16x32_bf16 v[84:87], v[144:147], v[176:179], v[84:87]
	v_mfma_f32_16x16x32_bf16 v[80:83], v[152:155], v[176:179], v[80:83]
	v_mfma_f32_16x16x32_bf16 v[68:71], v[144:147], v[194:197], v[68:71]
	v_mfma_f32_16x16x32_bf16 v[64:67], v[152:155], v[194:197], v[64:67]
	v_mfma_f32_16x16x32_bf16 v[132:135], v[148:151], v[164:167], v[132:135]
	v_mfma_f32_16x16x32_bf16 v[128:131], v[156:159], v[164:167], v[128:131]
	v_mfma_f32_16x16x32_bf16 v[116:119], v[148:151], v[172:175], v[116:119]
	v_mfma_f32_16x16x32_bf16 v[112:115], v[156:159], v[172:175], v[112:115]
	v_mfma_f32_16x16x32_bf16 v[84:87], v[148:151], v[190:193], v[84:87]
	v_mfma_f32_16x16x32_bf16 v[80:83], v[156:159], v[190:193], v[80:83]
	v_mfma_f32_16x16x32_bf16 v[68:71], v[148:151], v[198:201], v[68:71]
	v_mfma_f32_16x16x32_bf16 v[64:67], v[156:159], v[198:201], v[64:67]
	s_setprio 0
	s_barrier
	s_add_i32 s36, s61, s77
	v_lshl_add_u64 v[202:203], v[202:203], 0, s[94:95]
	s_mov_b32 m0, s36
	ds_read_b128 v[160:163], v221 offset:49152
	ds_read_b128 v[164:167], v221 offset:50176
	ds_read_b128 v[168:171], v221 offset:51200
	ds_read_b128 v[172:175], v221 offset:52224
	ds_read_b128 v[176:179], v221 offset:53248
	ds_read_b128 v[190:193], v221 offset:54272
	ds_read_b128 v[194:197], v221 offset:55296
	ds_read_b128 v[198:201], v221 offset:56320
	global_load_lds_dwordx4 v[202:203], off
	s_add_i32 m0, s36, 0x2000
	s_add_u32 s34, s34, 0x100080
	v_lshl_add_u64 v[202:203], v[204:205], 0, s[94:95]
	s_addc_u32 s35, s35, 0
	s_add_i32 s36, s62, s77
	global_load_lds_dwordx4 v[202:203], off
	v_lshl_add_u64 v[202:203], s[34:35], 0, v[232:233]
	s_mov_b32 m0, s36
	s_nop 0
	global_load_lds_dwordx4 v[202:203], off
	v_lshl_add_u64 v[202:203], s[34:35], 0, v[184:185]
	s_add_i32 m0, s36, 0x2000
	s_nop 0
	global_load_lds_dwordx4 v[202:203], off
	v_lshl_add_u64 v[202:203], v[206:207], 0, s[94:95]
	s_mov_b32 m0, s52
	s_nop 0
	global_load_lds_dwordx4 v[202:203], off
	v_lshl_add_u64 v[202:203], v[208:209], 0, s[94:95]
	s_mov_b32 m0, s53
	s_nop 0
	global_load_lds_dwordx4 v[202:203], off
	s_waitcnt vmcnt(8)
	s_waitcnt lgkmcnt(0)
	s_barrier
	s_setprio 1
	s_waitcnt lgkmcnt(0)
	v_mfma_f32_16x16x32_bf16 v[60:63], v[88:91], v[160:163], v[60:63]
	v_mfma_f32_16x16x32_bf16 v[56:59], v[96:99], v[160:163], v[56:59]
	v_mfma_f32_16x16x32_bf16 v[44:47], v[88:91], v[168:171], v[44:47]
	v_mfma_f32_16x16x32_bf16 v[40:43], v[96:99], v[168:171], v[40:43]
	v_mfma_f32_16x16x32_bf16 v[28:31], v[88:91], v[176:179], v[28:31]
	v_mfma_f32_16x16x32_bf16 v[24:27], v[96:99], v[176:179], v[24:27]
	v_mfma_f32_16x16x32_bf16 v[12:15], v[88:91], v[194:197], v[12:15]
	v_mfma_f32_16x16x32_bf16 v[8:11], v[96:99], v[194:197], v[8:11]
	v_mfma_f32_16x16x32_bf16 v[60:63], v[92:95], v[164:167], v[60:63]
	v_mfma_f32_16x16x32_bf16 v[56:59], v[100:103], v[164:167], v[56:59]
	v_mfma_f32_16x16x32_bf16 v[44:47], v[92:95], v[172:175], v[44:47]
	v_mfma_f32_16x16x32_bf16 v[40:43], v[100:103], v[172:175], v[40:43]
	v_mfma_f32_16x16x32_bf16 v[28:31], v[92:95], v[190:193], v[28:31]
	v_mfma_f32_16x16x32_bf16 v[24:27], v[100:103], v[190:193], v[24:27]
	v_mfma_f32_16x16x32_bf16 v[12:15], v[92:95], v[198:201], v[12:15]
	v_mfma_f32_16x16x32_bf16 v[8:11], v[100:103], v[198:201], v[8:11]
	s_setprio 0
	s_setprio 1
	v_mfma_f32_16x16x32_bf16 v[52:55], v[144:147], v[160:163], v[52:55]
	v_mfma_f32_16x16x32_bf16 v[48:51], v[152:155], v[160:163], v[48:51]
	v_mfma_f32_16x16x32_bf16 v[36:39], v[144:147], v[168:171], v[36:39]
	v_mfma_f32_16x16x32_bf16 v[32:35], v[152:155], v[168:171], v[32:35]
	v_mfma_f32_16x16x32_bf16 v[20:23], v[144:147], v[176:179], v[20:23]
	v_mfma_f32_16x16x32_bf16 v[16:19], v[152:155], v[176:179], v[16:19]
	v_mfma_f32_16x16x32_bf16 v[4:7], v[144:147], v[194:197], v[4:7]
	v_mfma_f32_16x16x32_bf16 v[0:3], v[152:155], v[194:197], v[0:3]
	v_mfma_f32_16x16x32_bf16 v[52:55], v[148:151], v[164:167], v[52:55]
	v_mfma_f32_16x16x32_bf16 v[48:51], v[156:159], v[164:167], v[48:51]
	v_mfma_f32_16x16x32_bf16 v[36:39], v[148:151], v[172:175], v[36:39]
	v_mfma_f32_16x16x32_bf16 v[32:35], v[156:159], v[172:175], v[32:35]
	v_mfma_f32_16x16x32_bf16 v[20:23], v[148:151], v[190:193], v[20:23]
	v_mfma_f32_16x16x32_bf16 v[16:19], v[156:159], v[190:193], v[16:19]
	v_mfma_f32_16x16x32_bf16 v[4:7], v[148:151], v[198:201], v[4:7]
	v_mfma_f32_16x16x32_bf16 v[0:3], v[156:159], v[198:201], v[0:3]
	s_setprio 0
	s_barrier
	s_add_i32 s60, s60, 2
	s_add_u32 s58, s58, 0x100
	s_addc_u32 s59, s59, 0
	s_add_u32 s30, s30, 0x100
	s_addc_u32 s31, s31, 0
	s_cmp_gt_u32 s60, 61
	s_cbranch_scc0 .LBB0_1492
	s_and_b64 vcc, exec, s[18:19]
	s_cbranch_vccz .LBB0_1495
	s_barrier
